# p3a GLU epilogue rewritten: 64-step serialized load/compute/store chain replaced by batched loads (24 per group, one group ahead), same per-element arithmetic
# speedup vs baseline: 1.1173x; 1.0137x over previous
.LBB0_1655:
	s_waitcnt vmcnt(0)
	v_readlane_b32 s44, v251, 23
	v_readlane_b32 s50, v251, 29
	v_readlane_b32 s51, v251, 30
	s_mov_b64 s[42:43], s[50:51]
	v_ashrrev_i32_e32 v64, 1, v144
	v_and_b32_e32 v64, 0xffffffc0, v64
	v_add_u32_e32 v66, s2, v64
	v_lshrrev_b32_e32 v67, 3, v144
	v_and_b32_e32 v64, 0x5f, v144
	v_and_or_b32 v68, v67, 4, v66
	v_or_b32_e32 v64, s41, v64
	v_lshlrev_b32_e32 v65, 10, v68
	v_lshl_add_u32 v65, v64, 1, v65
	v_lshlrev_b32_e32 v74, 2, v64
	global_load_dword v68, v74, s[42:43] offset:0
	global_load_dword v69, v74, s[42:43] offset:128
	v_mov_b32_e32 v66, v65
	global_load_ushort v190, v66, s[0:1]
	global_load_ushort v191, v66, s[4:5]
	global_load_ushort v192, v66, s[6:7]
	global_load_ushort v193, v66, s[0:1] offset:64
	global_load_ushort v194, v66, s[4:5] offset:64
	global_load_ushort v195, v66, s[6:7] offset:64
	global_load_ushort v196, v66, s[0:1] offset:1024
	global_load_ushort v197, v66, s[4:5] offset:1024
	global_load_ushort v198, v66, s[6:7] offset:1024
	global_load_ushort v199, v66, s[0:1] offset:1088
	global_load_ushort v200, v66, s[4:5] offset:1088
	global_load_ushort v201, v66, s[6:7] offset:1088
	global_load_ushort v202, v66, s[0:1] offset:2048
	global_load_ushort v203, v66, s[4:5] offset:2048
	global_load_ushort v204, v66, s[6:7] offset:2048
	global_load_ushort v205, v66, s[0:1] offset:2112
	global_load_ushort v206, v66, s[4:5] offset:2112
	global_load_ushort v207, v66, s[6:7] offset:2112
	global_load_ushort v208, v66, s[0:1] offset:3072
	global_load_ushort v209, v66, s[4:5] offset:3072
	global_load_ushort v210, v66, s[6:7] offset:3072
	global_load_ushort v211, v66, s[0:1] offset:3136
	global_load_ushort v212, v66, s[4:5] offset:3136
	global_load_ushort v213, v66, s[6:7] offset:3136
	v_add_u32_e32 v67, 0x2000, v65
	global_load_ushort v214, v67, s[0:1]
	global_load_ushort v215, v67, s[4:5]
	global_load_ushort v216, v67, s[6:7]
	global_load_ushort v217, v67, s[0:1] offset:64
	global_load_ushort v218, v67, s[4:5] offset:64
	global_load_ushort v219, v67, s[6:7] offset:64
	global_load_ushort v220, v67, s[0:1] offset:1024
	global_load_ushort v221, v67, s[4:5] offset:1024
	global_load_ushort v222, v67, s[6:7] offset:1024
	global_load_ushort v223, v67, s[0:1] offset:1088
	global_load_ushort v224, v67, s[4:5] offset:1088
	global_load_ushort v225, v67, s[6:7] offset:1088
	global_load_ushort v226, v67, s[0:1] offset:2048
	global_load_ushort v227, v67, s[4:5] offset:2048
	global_load_ushort v228, v67, s[6:7] offset:2048
	global_load_ushort v229, v67, s[0:1] offset:2112
	global_load_ushort v230, v67, s[4:5] offset:2112
	global_load_ushort v231, v67, s[6:7] offset:2112
	global_load_ushort v232, v67, s[0:1] offset:3072
	global_load_ushort v233, v67, s[4:5] offset:3072
	global_load_ushort v70, v67, s[6:7] offset:3072
	global_load_ushort v71, v67, s[0:1] offset:3136
	global_load_ushort v72, v67, s[4:5] offset:3136
	global_load_ushort v73, v67, s[6:7] offset:3136
	s_waitcnt vmcnt(48)
	s_waitcnt vmcnt(45)
	v_lshlrev_b32_e32 v190, 16, v190
	v_lshlrev_b32_e32 v191, 16, v191
	v_lshlrev_b32_e32 v192, 16, v192
	v_fmac_f32_e32 v191, v68, v190
	v_add_f32_e32 v190, v191, v192
	v_mul_f32_e32 v191, 0x3d372713, v190
	v_mul_f32_e32 v191, v190, v191
	v_fma_f32 v191, v190, v191, v190
	v_mul_f32_e32 v191, 0xbfcc422a, v191
	v_mul_f32_e32 v191, 0x3fb8aa3b, v191
	v_exp_f32_e32 v191, v191
	v_mul_f32_e32 v48, 0xbfb8aa3b, v48
	v_exp_f32_e32 v48, v48
	v_add_f32_e32 v191, 1.0, v191
	v_add_f32_e32 v48, 1.0, v48
	v_rcp_f32_e32 v191, v191
	v_rcp_f32_e32 v48, v48
	v_mul_f32_e32 v190, v190, v191
	v_mul_f32_e32 v190, v48, v190
	v_cvt_pk_bf16_f32 v190, v190, v190
	global_store_short v66, v190, s[10:11]
	s_waitcnt vmcnt(43)
	v_lshlrev_b32_e32 v193, 16, v193
	v_lshlrev_b32_e32 v194, 16, v194
	v_lshlrev_b32_e32 v195, 16, v195
	v_fmac_f32_e32 v194, v69, v193
	v_add_f32_e32 v193, v194, v195
	v_mul_f32_e32 v194, 0x3d372713, v193
	v_mul_f32_e32 v194, v193, v194
	v_fma_f32 v194, v193, v194, v193
	v_mul_f32_e32 v194, 0xbfcc422a, v194
	v_mul_f32_e32 v194, 0x3fb8aa3b, v194
	v_exp_f32_e32 v194, v194
	v_mul_f32_e32 v32, 0xbfb8aa3b, v32
	v_exp_f32_e32 v32, v32
	v_add_f32_e32 v194, 1.0, v194
	v_add_f32_e32 v32, 1.0, v32
	v_rcp_f32_e32 v194, v194
	v_rcp_f32_e32 v32, v32
	v_mul_f32_e32 v193, v193, v194
	v_mul_f32_e32 v193, v32, v193
	v_cvt_pk_bf16_f32 v193, v193, v193
	global_store_short v66, v193, s[10:11] offset:64
	s_waitcnt vmcnt(41)
	v_lshlrev_b32_e32 v196, 16, v196
	v_lshlrev_b32_e32 v197, 16, v197
	v_lshlrev_b32_e32 v198, 16, v198
	v_fmac_f32_e32 v197, v68, v196
	v_add_f32_e32 v196, v197, v198
	v_mul_f32_e32 v197, 0x3d372713, v196
	v_mul_f32_e32 v197, v196, v197
	v_fma_f32 v197, v196, v197, v196
	v_mul_f32_e32 v197, 0xbfcc422a, v197
	v_mul_f32_e32 v197, 0x3fb8aa3b, v197
	v_exp_f32_e32 v197, v197
	v_mul_f32_e32 v49, 0xbfb8aa3b, v49
	v_exp_f32_e32 v49, v49
	v_add_f32_e32 v197, 1.0, v197
	v_add_f32_e32 v49, 1.0, v49
	v_rcp_f32_e32 v197, v197
	v_rcp_f32_e32 v49, v49
	v_mul_f32_e32 v196, v196, v197
	v_mul_f32_e32 v196, v49, v196
	v_cvt_pk_bf16_f32 v196, v196, v196
	global_store_short v66, v196, s[10:11] offset:1024
	s_waitcnt vmcnt(39)
	v_lshlrev_b32_e32 v199, 16, v199
	v_lshlrev_b32_e32 v200, 16, v200
	v_lshlrev_b32_e32 v201, 16, v201
	v_fmac_f32_e32 v200, v69, v199
	v_add_f32_e32 v199, v200, v201
	v_mul_f32_e32 v200, 0x3d372713, v199
	v_mul_f32_e32 v200, v199, v200
	v_fma_f32 v200, v199, v200, v199
	v_mul_f32_e32 v200, 0xbfcc422a, v200
	v_mul_f32_e32 v200, 0x3fb8aa3b, v200
	v_exp_f32_e32 v200, v200
	v_mul_f32_e32 v33, 0xbfb8aa3b, v33
	v_exp_f32_e32 v33, v33
	v_add_f32_e32 v200, 1.0, v200
	v_add_f32_e32 v33, 1.0, v33
	v_rcp_f32_e32 v200, v200
	v_rcp_f32_e32 v33, v33
	v_mul_f32_e32 v199, v199, v200
	v_mul_f32_e32 v199, v33, v199
	v_cvt_pk_bf16_f32 v199, v199, v199
	global_store_short v66, v199, s[10:11] offset:1088
	s_waitcnt vmcnt(37)
	v_lshlrev_b32_e32 v202, 16, v202
	v_lshlrev_b32_e32 v203, 16, v203
	v_lshlrev_b32_e32 v204, 16, v204
	v_fmac_f32_e32 v203, v68, v202
	v_add_f32_e32 v202, v203, v204
	v_mul_f32_e32 v203, 0x3d372713, v202
	v_mul_f32_e32 v203, v202, v203
	v_fma_f32 v203, v202, v203, v202
	v_mul_f32_e32 v203, 0xbfcc422a, v203
	v_mul_f32_e32 v203, 0x3fb8aa3b, v203
	v_exp_f32_e32 v203, v203
	v_mul_f32_e32 v50, 0xbfb8aa3b, v50
	v_exp_f32_e32 v50, v50
	v_add_f32_e32 v203, 1.0, v203
	v_add_f32_e32 v50, 1.0, v50
	v_rcp_f32_e32 v203, v203
	v_rcp_f32_e32 v50, v50
	v_mul_f32_e32 v202, v202, v203
	v_mul_f32_e32 v202, v50, v202
	v_cvt_pk_bf16_f32 v202, v202, v202
	global_store_short v66, v202, s[10:11] offset:2048
	s_waitcnt vmcnt(35)
	v_lshlrev_b32_e32 v205, 16, v205
	v_lshlrev_b32_e32 v206, 16, v206
	v_lshlrev_b32_e32 v207, 16, v207
	v_fmac_f32_e32 v206, v69, v205
	v_add_f32_e32 v205, v206, v207
	v_mul_f32_e32 v206, 0x3d372713, v205
	v_mul_f32_e32 v206, v205, v206
	v_fma_f32 v206, v205, v206, v205
	v_mul_f32_e32 v206, 0xbfcc422a, v206
	v_mul_f32_e32 v206, 0x3fb8aa3b, v206
	v_exp_f32_e32 v206, v206
	v_mul_f32_e32 v34, 0xbfb8aa3b, v34
	v_exp_f32_e32 v34, v34
	v_add_f32_e32 v206, 1.0, v206
	v_add_f32_e32 v34, 1.0, v34
	v_rcp_f32_e32 v206, v206
	v_rcp_f32_e32 v34, v34
	v_mul_f32_e32 v205, v205, v206
	v_mul_f32_e32 v205, v34, v205
	v_cvt_pk_bf16_f32 v205, v205, v205
	global_store_short v66, v205, s[10:11] offset:2112
	s_waitcnt vmcnt(33)
	v_lshlrev_b32_e32 v208, 16, v208
	v_lshlrev_b32_e32 v209, 16, v209
	v_lshlrev_b32_e32 v210, 16, v210
	v_fmac_f32_e32 v209, v68, v208
	v_add_f32_e32 v208, v209, v210
	v_mul_f32_e32 v209, 0x3d372713, v208
	v_mul_f32_e32 v209, v208, v209
	v_fma_f32 v209, v208, v209, v208
	v_mul_f32_e32 v209, 0xbfcc422a, v209
	v_mul_f32_e32 v209, 0x3fb8aa3b, v209
	v_exp_f32_e32 v209, v209
	v_mul_f32_e32 v51, 0xbfb8aa3b, v51
	v_exp_f32_e32 v51, v51
	v_add_f32_e32 v209, 1.0, v209
	v_add_f32_e32 v51, 1.0, v51
	v_rcp_f32_e32 v209, v209
	v_rcp_f32_e32 v51, v51
	v_mul_f32_e32 v208, v208, v209
	v_mul_f32_e32 v208, v51, v208
	v_cvt_pk_bf16_f32 v208, v208, v208
	global_store_short v66, v208, s[10:11] offset:3072
	s_waitcnt vmcnt(31)
	v_lshlrev_b32_e32 v211, 16, v211
	v_lshlrev_b32_e32 v212, 16, v212
	v_lshlrev_b32_e32 v213, 16, v213
	v_fmac_f32_e32 v212, v69, v211
	v_add_f32_e32 v211, v212, v213
	v_mul_f32_e32 v212, 0x3d372713, v211
	v_mul_f32_e32 v212, v211, v212
	v_fma_f32 v212, v211, v212, v211
	v_mul_f32_e32 v212, 0xbfcc422a, v212
	v_mul_f32_e32 v212, 0x3fb8aa3b, v212
	v_exp_f32_e32 v212, v212
	v_mul_f32_e32 v35, 0xbfb8aa3b, v35
	v_exp_f32_e32 v35, v35
	v_add_f32_e32 v212, 1.0, v212
	v_add_f32_e32 v35, 1.0, v35
	v_rcp_f32_e32 v212, v212
	v_rcp_f32_e32 v35, v35
	v_mul_f32_e32 v211, v211, v212
	v_mul_f32_e32 v211, v35, v211
	v_cvt_pk_bf16_f32 v211, v211, v211
	global_store_short v66, v211, s[10:11] offset:3136
	v_add_u32_e32 v66, 0x4000, v65
	global_load_ushort v190, v66, s[0:1]
	global_load_ushort v191, v66, s[4:5]
	global_load_ushort v192, v66, s[6:7]
	global_load_ushort v193, v66, s[0:1] offset:64
	global_load_ushort v194, v66, s[4:5] offset:64
	global_load_ushort v195, v66, s[6:7] offset:64
	global_load_ushort v196, v66, s[0:1] offset:1024
	global_load_ushort v197, v66, s[4:5] offset:1024
	global_load_ushort v198, v66, s[6:7] offset:1024
	global_load_ushort v199, v66, s[0:1] offset:1088
	global_load_ushort v200, v66, s[4:5] offset:1088
	global_load_ushort v201, v66, s[6:7] offset:1088
	global_load_ushort v202, v66, s[0:1] offset:2048
	global_load_ushort v203, v66, s[4:5] offset:2048
	global_load_ushort v204, v66, s[6:7] offset:2048
	global_load_ushort v205, v66, s[0:1] offset:2112
	global_load_ushort v206, v66, s[4:5] offset:2112
	global_load_ushort v207, v66, s[6:7] offset:2112
	global_load_ushort v208, v66, s[0:1] offset:3072
	global_load_ushort v209, v66, s[4:5] offset:3072
	global_load_ushort v210, v66, s[6:7] offset:3072
	global_load_ushort v211, v66, s[0:1] offset:3136
	global_load_ushort v212, v66, s[4:5] offset:3136
	global_load_ushort v213, v66, s[6:7] offset:3136
	s_waitcnt vmcnt(53)
	v_lshlrev_b32_e32 v214, 16, v214
	v_lshlrev_b32_e32 v215, 16, v215
	v_lshlrev_b32_e32 v216, 16, v216
	v_fmac_f32_e32 v215, v68, v214
	v_add_f32_e32 v214, v215, v216
	v_mul_f32_e32 v215, 0x3d372713, v214
	v_mul_f32_e32 v215, v214, v215
	v_fma_f32 v215, v214, v215, v214
	v_mul_f32_e32 v215, 0xbfcc422a, v215
	v_mul_f32_e32 v215, 0x3fb8aa3b, v215
	v_exp_f32_e32 v215, v215
	v_mul_f32_e32 v52, 0xbfb8aa3b, v52
	v_exp_f32_e32 v52, v52
	v_add_f32_e32 v215, 1.0, v215
	v_add_f32_e32 v52, 1.0, v52
	v_rcp_f32_e32 v215, v215
	v_rcp_f32_e32 v52, v52
	v_mul_f32_e32 v214, v214, v215
	v_mul_f32_e32 v214, v52, v214
	v_cvt_pk_bf16_f32 v214, v214, v214
	global_store_short v67, v214, s[10:11]
	s_waitcnt vmcnt(51)
	v_lshlrev_b32_e32 v217, 16, v217
	v_lshlrev_b32_e32 v218, 16, v218
	v_lshlrev_b32_e32 v219, 16, v219
	v_fmac_f32_e32 v218, v69, v217
	v_add_f32_e32 v217, v218, v219
	v_mul_f32_e32 v218, 0x3d372713, v217
	v_mul_f32_e32 v218, v217, v218
	v_fma_f32 v218, v217, v218, v217
	v_mul_f32_e32 v218, 0xbfcc422a, v218
	v_mul_f32_e32 v218, 0x3fb8aa3b, v218
	v_exp_f32_e32 v218, v218
	v_mul_f32_e32 v36, 0xbfb8aa3b, v36
	v_exp_f32_e32 v36, v36
	v_add_f32_e32 v218, 1.0, v218
	v_add_f32_e32 v36, 1.0, v36
	v_rcp_f32_e32 v218, v218
	v_rcp_f32_e32 v36, v36
	v_mul_f32_e32 v217, v217, v218
	v_mul_f32_e32 v217, v36, v217
	v_cvt_pk_bf16_f32 v217, v217, v217
	global_store_short v67, v217, s[10:11] offset:64
	s_waitcnt vmcnt(49)
	v_lshlrev_b32_e32 v220, 16, v220
	v_lshlrev_b32_e32 v221, 16, v221
	v_lshlrev_b32_e32 v222, 16, v222
	v_fmac_f32_e32 v221, v68, v220
	v_add_f32_e32 v220, v221, v222
	v_mul_f32_e32 v221, 0x3d372713, v220
	v_mul_f32_e32 v221, v220, v221
	v_fma_f32 v221, v220, v221, v220
	v_mul_f32_e32 v221, 0xbfcc422a, v221
	v_mul_f32_e32 v221, 0x3fb8aa3b, v221
	v_exp_f32_e32 v221, v221
	v_mul_f32_e32 v53, 0xbfb8aa3b, v53
	v_exp_f32_e32 v53, v53
	v_add_f32_e32 v221, 1.0, v221
	v_add_f32_e32 v53, 1.0, v53
	v_rcp_f32_e32 v221, v221
	v_rcp_f32_e32 v53, v53
	v_mul_f32_e32 v220, v220, v221
	v_mul_f32_e32 v220, v53, v220
	v_cvt_pk_bf16_f32 v220, v220, v220
	global_store_short v67, v220, s[10:11] offset:1024
	s_waitcnt vmcnt(47)
	v_lshlrev_b32_e32 v223, 16, v223
	v_lshlrev_b32_e32 v224, 16, v224
	v_lshlrev_b32_e32 v225, 16, v225
	v_fmac_f32_e32 v224, v69, v223
	v_add_f32_e32 v223, v224, v225
	v_mul_f32_e32 v224, 0x3d372713, v223
	v_mul_f32_e32 v224, v223, v224
	v_fma_f32 v224, v223, v224, v223
	v_mul_f32_e32 v224, 0xbfcc422a, v224
	v_mul_f32_e32 v224, 0x3fb8aa3b, v224
	v_exp_f32_e32 v224, v224
	v_mul_f32_e32 v37, 0xbfb8aa3b, v37
	v_exp_f32_e32 v37, v37
	v_add_f32_e32 v224, 1.0, v224
	v_add_f32_e32 v37, 1.0, v37
	v_rcp_f32_e32 v224, v224
	v_rcp_f32_e32 v37, v37
	v_mul_f32_e32 v223, v223, v224
	v_mul_f32_e32 v223, v37, v223
	v_cvt_pk_bf16_f32 v223, v223, v223
	global_store_short v67, v223, s[10:11] offset:1088
	s_waitcnt vmcnt(45)
	v_lshlrev_b32_e32 v226, 16, v226
	v_lshlrev_b32_e32 v227, 16, v227
	v_lshlrev_b32_e32 v228, 16, v228
	v_fmac_f32_e32 v227, v68, v226
	v_add_f32_e32 v226, v227, v228
	v_mul_f32_e32 v227, 0x3d372713, v226
	v_mul_f32_e32 v227, v226, v227
	v_fma_f32 v227, v226, v227, v226
	v_mul_f32_e32 v227, 0xbfcc422a, v227
	v_mul_f32_e32 v227, 0x3fb8aa3b, v227
	v_exp_f32_e32 v227, v227
	v_mul_f32_e32 v54, 0xbfb8aa3b, v54
	v_exp_f32_e32 v54, v54
	v_add_f32_e32 v227, 1.0, v227
	v_add_f32_e32 v54, 1.0, v54
	v_rcp_f32_e32 v227, v227
	v_rcp_f32_e32 v54, v54
	v_mul_f32_e32 v226, v226, v227
	v_mul_f32_e32 v226, v54, v226
	v_cvt_pk_bf16_f32 v226, v226, v226
	global_store_short v67, v226, s[10:11] offset:2048
	s_waitcnt vmcnt(43)
	v_lshlrev_b32_e32 v229, 16, v229
	v_lshlrev_b32_e32 v230, 16, v230
	v_lshlrev_b32_e32 v231, 16, v231
	v_fmac_f32_e32 v230, v69, v229
	v_add_f32_e32 v229, v230, v231
	v_mul_f32_e32 v230, 0x3d372713, v229
	v_mul_f32_e32 v230, v229, v230
	v_fma_f32 v230, v229, v230, v229
	v_mul_f32_e32 v230, 0xbfcc422a, v230
	v_mul_f32_e32 v230, 0x3fb8aa3b, v230
	v_exp_f32_e32 v230, v230
	v_mul_f32_e32 v38, 0xbfb8aa3b, v38
	v_exp_f32_e32 v38, v38
	v_add_f32_e32 v230, 1.0, v230
	v_add_f32_e32 v38, 1.0, v38
	v_rcp_f32_e32 v230, v230
	v_rcp_f32_e32 v38, v38
	v_mul_f32_e32 v229, v229, v230
	v_mul_f32_e32 v229, v38, v229
	v_cvt_pk_bf16_f32 v229, v229, v229
	global_store_short v67, v229, s[10:11] offset:2112
	s_waitcnt vmcnt(41)
	v_lshlrev_b32_e32 v232, 16, v232
	v_lshlrev_b32_e32 v233, 16, v233
	v_lshlrev_b32_e32 v70, 16, v70
	v_fmac_f32_e32 v233, v68, v232
	v_add_f32_e32 v232, v233, v70
	v_mul_f32_e32 v233, 0x3d372713, v232
	v_mul_f32_e32 v233, v232, v233
	v_fma_f32 v233, v232, v233, v232
	v_mul_f32_e32 v233, 0xbfcc422a, v233
	v_mul_f32_e32 v233, 0x3fb8aa3b, v233
	v_exp_f32_e32 v233, v233
	v_mul_f32_e32 v55, 0xbfb8aa3b, v55
	v_exp_f32_e32 v55, v55
	v_add_f32_e32 v233, 1.0, v233
	v_add_f32_e32 v55, 1.0, v55
	v_rcp_f32_e32 v233, v233
	v_rcp_f32_e32 v55, v55
	v_mul_f32_e32 v232, v232, v233
	v_mul_f32_e32 v232, v55, v232
	v_cvt_pk_bf16_f32 v232, v232, v232
	global_store_short v67, v232, s[10:11] offset:3072
	s_waitcnt vmcnt(39)
	v_lshlrev_b32_e32 v71, 16, v71
	v_lshlrev_b32_e32 v72, 16, v72
	v_lshlrev_b32_e32 v73, 16, v73
	v_fmac_f32_e32 v72, v69, v71
	v_add_f32_e32 v71, v72, v73
	v_mul_f32_e32 v72, 0x3d372713, v71
	v_mul_f32_e32 v72, v71, v72
	v_fma_f32 v72, v71, v72, v71
	v_mul_f32_e32 v72, 0xbfcc422a, v72
	v_mul_f32_e32 v72, 0x3fb8aa3b, v72
	v_exp_f32_e32 v72, v72
	v_mul_f32_e32 v39, 0xbfb8aa3b, v39
	v_exp_f32_e32 v39, v39
	v_add_f32_e32 v72, 1.0, v72
	v_add_f32_e32 v39, 1.0, v39
	v_rcp_f32_e32 v72, v72
	v_rcp_f32_e32 v39, v39
	v_mul_f32_e32 v71, v71, v72
	v_mul_f32_e32 v71, v39, v71
	v_cvt_pk_bf16_f32 v71, v71, v71
	global_store_short v67, v71, s[10:11] offset:3136
	v_add_u32_e32 v67, 0x6000, v65
	global_load_ushort v214, v67, s[0:1]
	global_load_ushort v215, v67, s[4:5]
	global_load_ushort v216, v67, s[6:7]
	global_load_ushort v217, v67, s[0:1] offset:64
	global_load_ushort v218, v67, s[4:5] offset:64
	global_load_ushort v219, v67, s[6:7] offset:64
	global_load_ushort v220, v67, s[0:1] offset:1024
	global_load_ushort v221, v67, s[4:5] offset:1024
	global_load_ushort v222, v67, s[6:7] offset:1024
	global_load_ushort v223, v67, s[0:1] offset:1088
	global_load_ushort v224, v67, s[4:5] offset:1088
	global_load_ushort v225, v67, s[6:7] offset:1088
	global_load_ushort v226, v67, s[0:1] offset:2048
	global_load_ushort v227, v67, s[4:5] offset:2048
	global_load_ushort v228, v67, s[6:7] offset:2048
	global_load_ushort v229, v67, s[0:1] offset:2112
	global_load_ushort v230, v67, s[4:5] offset:2112
	global_load_ushort v231, v67, s[6:7] offset:2112
	global_load_ushort v232, v67, s[0:1] offset:3072
	global_load_ushort v233, v67, s[4:5] offset:3072
	global_load_ushort v70, v67, s[6:7] offset:3072
	global_load_ushort v71, v67, s[0:1] offset:3136
	global_load_ushort v72, v67, s[4:5] offset:3136
	global_load_ushort v73, v67, s[6:7] offset:3136
	s_waitcnt vmcnt(53)
	v_lshlrev_b32_e32 v190, 16, v190
	v_lshlrev_b32_e32 v191, 16, v191
	v_lshlrev_b32_e32 v192, 16, v192
	v_fmac_f32_e32 v191, v68, v190
	v_add_f32_e32 v190, v191, v192
	v_mul_f32_e32 v191, 0x3d372713, v190
	v_mul_f32_e32 v191, v190, v191
	v_fma_f32 v191, v190, v191, v190
	v_mul_f32_e32 v191, 0xbfcc422a, v191
	v_mul_f32_e32 v191, 0x3fb8aa3b, v191
	v_exp_f32_e32 v191, v191
	v_mul_f32_e32 v56, 0xbfb8aa3b, v56
	v_exp_f32_e32 v56, v56
	v_add_f32_e32 v191, 1.0, v191
	v_add_f32_e32 v56, 1.0, v56
	v_rcp_f32_e32 v191, v191
	v_rcp_f32_e32 v56, v56
	v_mul_f32_e32 v190, v190, v191
	v_mul_f32_e32 v190, v56, v190
	v_cvt_pk_bf16_f32 v190, v190, v190
	global_store_short v66, v190, s[10:11]
	s_waitcnt vmcnt(51)
	v_lshlrev_b32_e32 v193, 16, v193
	v_lshlrev_b32_e32 v194, 16, v194
	v_lshlrev_b32_e32 v195, 16, v195
	v_fmac_f32_e32 v194, v69, v193
	v_add_f32_e32 v193, v194, v195
	v_mul_f32_e32 v194, 0x3d372713, v193
	v_mul_f32_e32 v194, v193, v194
	v_fma_f32 v194, v193, v194, v193
	v_mul_f32_e32 v194, 0xbfcc422a, v194
	v_mul_f32_e32 v194, 0x3fb8aa3b, v194
	v_exp_f32_e32 v194, v194
	v_mul_f32_e32 v40, 0xbfb8aa3b, v40
	v_exp_f32_e32 v40, v40
	v_add_f32_e32 v194, 1.0, v194
	v_add_f32_e32 v40, 1.0, v40
	v_rcp_f32_e32 v194, v194
	v_rcp_f32_e32 v40, v40
	v_mul_f32_e32 v193, v193, v194
	v_mul_f32_e32 v193, v40, v193
	v_cvt_pk_bf16_f32 v193, v193, v193
	global_store_short v66, v193, s[10:11] offset:64
	s_waitcnt vmcnt(49)
	v_lshlrev_b32_e32 v196, 16, v196
	v_lshlrev_b32_e32 v197, 16, v197
	v_lshlrev_b32_e32 v198, 16, v198
	v_fmac_f32_e32 v197, v68, v196
	v_add_f32_e32 v196, v197, v198
	v_mul_f32_e32 v197, 0x3d372713, v196
	v_mul_f32_e32 v197, v196, v197
	v_fma_f32 v197, v196, v197, v196
	v_mul_f32_e32 v197, 0xbfcc422a, v197
	v_mul_f32_e32 v197, 0x3fb8aa3b, v197
	v_exp_f32_e32 v197, v197
	v_mul_f32_e32 v57, 0xbfb8aa3b, v57
	v_exp_f32_e32 v57, v57
	v_add_f32_e32 v197, 1.0, v197
	v_add_f32_e32 v57, 1.0, v57
	v_rcp_f32_e32 v197, v197
	v_rcp_f32_e32 v57, v57
	v_mul_f32_e32 v196, v196, v197
	v_mul_f32_e32 v196, v57, v196
	v_cvt_pk_bf16_f32 v196, v196, v196
	global_store_short v66, v196, s[10:11] offset:1024
	s_waitcnt vmcnt(47)
	v_lshlrev_b32_e32 v199, 16, v199
	v_lshlrev_b32_e32 v200, 16, v200
	v_lshlrev_b32_e32 v201, 16, v201
	v_fmac_f32_e32 v200, v69, v199
	v_add_f32_e32 v199, v200, v201
	v_mul_f32_e32 v200, 0x3d372713, v199
	v_mul_f32_e32 v200, v199, v200
	v_fma_f32 v200, v199, v200, v199
	v_mul_f32_e32 v200, 0xbfcc422a, v200
	v_mul_f32_e32 v200, 0x3fb8aa3b, v200
	v_exp_f32_e32 v200, v200
	v_mul_f32_e32 v41, 0xbfb8aa3b, v41
	v_exp_f32_e32 v41, v41
	v_add_f32_e32 v200, 1.0, v200
	v_add_f32_e32 v41, 1.0, v41
	v_rcp_f32_e32 v200, v200
	v_rcp_f32_e32 v41, v41
	v_mul_f32_e32 v199, v199, v200
	v_mul_f32_e32 v199, v41, v199
	v_cvt_pk_bf16_f32 v199, v199, v199
	global_store_short v66, v199, s[10:11] offset:1088
	s_waitcnt vmcnt(45)
	v_lshlrev_b32_e32 v202, 16, v202
	v_lshlrev_b32_e32 v203, 16, v203
	v_lshlrev_b32_e32 v204, 16, v204
	v_fmac_f32_e32 v203, v68, v202
	v_add_f32_e32 v202, v203, v204
	v_mul_f32_e32 v203, 0x3d372713, v202
	v_mul_f32_e32 v203, v202, v203
	v_fma_f32 v203, v202, v203, v202
	v_mul_f32_e32 v203, 0xbfcc422a, v203
	v_mul_f32_e32 v203, 0x3fb8aa3b, v203
	v_exp_f32_e32 v203, v203
	v_mul_f32_e32 v58, 0xbfb8aa3b, v58
	v_exp_f32_e32 v58, v58
	v_add_f32_e32 v203, 1.0, v203
	v_add_f32_e32 v58, 1.0, v58
	v_rcp_f32_e32 v203, v203
	v_rcp_f32_e32 v58, v58
	v_mul_f32_e32 v202, v202, v203
	v_mul_f32_e32 v202, v58, v202
	v_cvt_pk_bf16_f32 v202, v202, v202
	global_store_short v66, v202, s[10:11] offset:2048
	s_waitcnt vmcnt(43)
	v_lshlrev_b32_e32 v205, 16, v205
	v_lshlrev_b32_e32 v206, 16, v206
	v_lshlrev_b32_e32 v207, 16, v207
	v_fmac_f32_e32 v206, v69, v205
	v_add_f32_e32 v205, v206, v207
	v_mul_f32_e32 v206, 0x3d372713, v205
	v_mul_f32_e32 v206, v205, v206
	v_fma_f32 v206, v205, v206, v205
	v_mul_f32_e32 v206, 0xbfcc422a, v206
	v_mul_f32_e32 v206, 0x3fb8aa3b, v206
	v_exp_f32_e32 v206, v206
	v_mul_f32_e32 v42, 0xbfb8aa3b, v42
	v_exp_f32_e32 v42, v42
	v_add_f32_e32 v206, 1.0, v206
	v_add_f32_e32 v42, 1.0, v42
	v_rcp_f32_e32 v206, v206
	v_rcp_f32_e32 v42, v42
	v_mul_f32_e32 v205, v205, v206
	v_mul_f32_e32 v205, v42, v205
	v_cvt_pk_bf16_f32 v205, v205, v205
	global_store_short v66, v205, s[10:11] offset:2112
	s_waitcnt vmcnt(41)
	v_lshlrev_b32_e32 v208, 16, v208
	v_lshlrev_b32_e32 v209, 16, v209
	v_lshlrev_b32_e32 v210, 16, v210
	v_fmac_f32_e32 v209, v68, v208
	v_add_f32_e32 v208, v209, v210
	v_mul_f32_e32 v209, 0x3d372713, v208
	v_mul_f32_e32 v209, v208, v209
	v_fma_f32 v209, v208, v209, v208
	v_mul_f32_e32 v209, 0xbfcc422a, v209
	v_mul_f32_e32 v209, 0x3fb8aa3b, v209
	v_exp_f32_e32 v209, v209
	v_mul_f32_e32 v59, 0xbfb8aa3b, v59
	v_exp_f32_e32 v59, v59
	v_add_f32_e32 v209, 1.0, v209
	v_add_f32_e32 v59, 1.0, v59
	v_rcp_f32_e32 v209, v209
	v_rcp_f32_e32 v59, v59
	v_mul_f32_e32 v208, v208, v209
	v_mul_f32_e32 v208, v59, v208
	v_cvt_pk_bf16_f32 v208, v208, v208
	global_store_short v66, v208, s[10:11] offset:3072
	s_waitcnt vmcnt(39)
	v_lshlrev_b32_e32 v211, 16, v211
	v_lshlrev_b32_e32 v212, 16, v212
	v_lshlrev_b32_e32 v213, 16, v213
	v_fmac_f32_e32 v212, v69, v211
	v_add_f32_e32 v211, v212, v213
	v_mul_f32_e32 v212, 0x3d372713, v211
	v_mul_f32_e32 v212, v211, v212
	v_fma_f32 v212, v211, v212, v211
	v_mul_f32_e32 v212, 0xbfcc422a, v212
	v_mul_f32_e32 v212, 0x3fb8aa3b, v212
	v_exp_f32_e32 v212, v212
	v_mul_f32_e32 v43, 0xbfb8aa3b, v43
	v_exp_f32_e32 v43, v43
	v_add_f32_e32 v212, 1.0, v212
	v_add_f32_e32 v43, 1.0, v43
	v_rcp_f32_e32 v212, v212
	v_rcp_f32_e32 v43, v43
	v_mul_f32_e32 v211, v211, v212
	v_mul_f32_e32 v211, v43, v211
	v_cvt_pk_bf16_f32 v211, v211, v211
	global_store_short v66, v211, s[10:11] offset:3136
	v_add_u32_e32 v66, 0x8000, v65
	global_load_ushort v190, v66, s[0:1]
	global_load_ushort v191, v66, s[4:5]
	global_load_ushort v192, v66, s[6:7]
	global_load_ushort v193, v66, s[0:1] offset:64
	global_load_ushort v194, v66, s[4:5] offset:64
	global_load_ushort v195, v66, s[6:7] offset:64
	global_load_ushort v196, v66, s[0:1] offset:1024
	global_load_ushort v197, v66, s[4:5] offset:1024
	global_load_ushort v198, v66, s[6:7] offset:1024
	global_load_ushort v199, v66, s[0:1] offset:1088
	global_load_ushort v200, v66, s[4:5] offset:1088
	global_load_ushort v201, v66, s[6:7] offset:1088
	global_load_ushort v202, v66, s[0:1] offset:2048
	global_load_ushort v203, v66, s[4:5] offset:2048
	global_load_ushort v204, v66, s[6:7] offset:2048
	global_load_ushort v205, v66, s[0:1] offset:2112
	global_load_ushort v206, v66, s[4:5] offset:2112
	global_load_ushort v207, v66, s[6:7] offset:2112
	global_load_ushort v208, v66, s[0:1] offset:3072
	global_load_ushort v209, v66, s[4:5] offset:3072
	global_load_ushort v210, v66, s[6:7] offset:3072
	global_load_ushort v211, v66, s[0:1] offset:3136
	global_load_ushort v212, v66, s[4:5] offset:3136
	global_load_ushort v213, v66, s[6:7] offset:3136
	s_waitcnt vmcnt(53)
	v_lshlrev_b32_e32 v214, 16, v214
	v_lshlrev_b32_e32 v215, 16, v215
	v_lshlrev_b32_e32 v216, 16, v216
	v_fmac_f32_e32 v215, v68, v214
	v_add_f32_e32 v214, v215, v216
	v_mul_f32_e32 v215, 0x3d372713, v214
	v_mul_f32_e32 v215, v214, v215
	v_fma_f32 v215, v214, v215, v214
	v_mul_f32_e32 v215, 0xbfcc422a, v215
	v_mul_f32_e32 v215, 0x3fb8aa3b, v215
	v_exp_f32_e32 v215, v215
	v_mul_f32_e32 v60, 0xbfb8aa3b, v60
	v_exp_f32_e32 v60, v60
	v_add_f32_e32 v215, 1.0, v215
	v_add_f32_e32 v60, 1.0, v60
	v_rcp_f32_e32 v215, v215
	v_rcp_f32_e32 v60, v60
	v_mul_f32_e32 v214, v214, v215
	v_mul_f32_e32 v214, v60, v214
	v_cvt_pk_bf16_f32 v214, v214, v214
	global_store_short v67, v214, s[10:11]
	s_waitcnt vmcnt(51)
	v_lshlrev_b32_e32 v217, 16, v217
	v_lshlrev_b32_e32 v218, 16, v218
	v_lshlrev_b32_e32 v219, 16, v219
	v_fmac_f32_e32 v218, v69, v217
	v_add_f32_e32 v217, v218, v219
	v_mul_f32_e32 v218, 0x3d372713, v217
	v_mul_f32_e32 v218, v217, v218
	v_fma_f32 v218, v217, v218, v217
	v_mul_f32_e32 v218, 0xbfcc422a, v218
	v_mul_f32_e32 v218, 0x3fb8aa3b, v218
	v_exp_f32_e32 v218, v218
	v_mul_f32_e32 v44, 0xbfb8aa3b, v44
	v_exp_f32_e32 v44, v44
	v_add_f32_e32 v218, 1.0, v218
	v_add_f32_e32 v44, 1.0, v44
	v_rcp_f32_e32 v218, v218
	v_rcp_f32_e32 v44, v44
	v_mul_f32_e32 v217, v217, v218
	v_mul_f32_e32 v217, v44, v217
	v_cvt_pk_bf16_f32 v217, v217, v217
	global_store_short v67, v217, s[10:11] offset:64
	s_waitcnt vmcnt(49)
	v_lshlrev_b32_e32 v220, 16, v220
	v_lshlrev_b32_e32 v221, 16, v221
	v_lshlrev_b32_e32 v222, 16, v222
	v_fmac_f32_e32 v221, v68, v220
	v_add_f32_e32 v220, v221, v222
	v_mul_f32_e32 v221, 0x3d372713, v220
	v_mul_f32_e32 v221, v220, v221
	v_fma_f32 v221, v220, v221, v220
	v_mul_f32_e32 v221, 0xbfcc422a, v221
	v_mul_f32_e32 v221, 0x3fb8aa3b, v221
	v_exp_f32_e32 v221, v221
	v_mul_f32_e32 v61, 0xbfb8aa3b, v61
	v_exp_f32_e32 v61, v61
	v_add_f32_e32 v221, 1.0, v221
	v_add_f32_e32 v61, 1.0, v61
	v_rcp_f32_e32 v221, v221
	v_rcp_f32_e32 v61, v61
	v_mul_f32_e32 v220, v220, v221
	v_mul_f32_e32 v220, v61, v220
	v_cvt_pk_bf16_f32 v220, v220, v220
	global_store_short v67, v220, s[10:11] offset:1024
	s_waitcnt vmcnt(47)
	v_lshlrev_b32_e32 v223, 16, v223
	v_lshlrev_b32_e32 v224, 16, v224
	v_lshlrev_b32_e32 v225, 16, v225
	v_fmac_f32_e32 v224, v69, v223
	v_add_f32_e32 v223, v224, v225
	v_mul_f32_e32 v224, 0x3d372713, v223
	v_mul_f32_e32 v224, v223, v224
	v_fma_f32 v224, v223, v224, v223
	v_mul_f32_e32 v224, 0xbfcc422a, v224
	v_mul_f32_e32 v224, 0x3fb8aa3b, v224
	v_exp_f32_e32 v224, v224
	v_mul_f32_e32 v45, 0xbfb8aa3b, v45
	v_exp_f32_e32 v45, v45
	v_add_f32_e32 v224, 1.0, v224
	v_add_f32_e32 v45, 1.0, v45
	v_rcp_f32_e32 v224, v224
	v_rcp_f32_e32 v45, v45
	v_mul_f32_e32 v223, v223, v224
	v_mul_f32_e32 v223, v45, v223
	v_cvt_pk_bf16_f32 v223, v223, v223
	global_store_short v67, v223, s[10:11] offset:1088
	s_waitcnt vmcnt(45)
	v_lshlrev_b32_e32 v226, 16, v226
	v_lshlrev_b32_e32 v227, 16, v227
	v_lshlrev_b32_e32 v228, 16, v228
	v_fmac_f32_e32 v227, v68, v226
	v_add_f32_e32 v226, v227, v228
	v_mul_f32_e32 v227, 0x3d372713, v226
	v_mul_f32_e32 v227, v226, v227
	v_fma_f32 v227, v226, v227, v226
	v_mul_f32_e32 v227, 0xbfcc422a, v227
	v_mul_f32_e32 v227, 0x3fb8aa3b, v227
	v_exp_f32_e32 v227, v227
	v_mul_f32_e32 v62, 0xbfb8aa3b, v62
	v_exp_f32_e32 v62, v62
	v_add_f32_e32 v227, 1.0, v227
	v_add_f32_e32 v62, 1.0, v62
	v_rcp_f32_e32 v227, v227
	v_rcp_f32_e32 v62, v62
	v_mul_f32_e32 v226, v226, v227
	v_mul_f32_e32 v226, v62, v226
	v_cvt_pk_bf16_f32 v226, v226, v226
	global_store_short v67, v226, s[10:11] offset:2048
	s_waitcnt vmcnt(43)
	v_lshlrev_b32_e32 v229, 16, v229
	v_lshlrev_b32_e32 v230, 16, v230
	v_lshlrev_b32_e32 v231, 16, v231
	v_fmac_f32_e32 v230, v69, v229
	v_add_f32_e32 v229, v230, v231
	v_mul_f32_e32 v230, 0x3d372713, v229
	v_mul_f32_e32 v230, v229, v230
	v_fma_f32 v230, v229, v230, v229
	v_mul_f32_e32 v230, 0xbfcc422a, v230
	v_mul_f32_e32 v230, 0x3fb8aa3b, v230
	v_exp_f32_e32 v230, v230
	v_mul_f32_e32 v46, 0xbfb8aa3b, v46
	v_exp_f32_e32 v46, v46
	v_add_f32_e32 v230, 1.0, v230
	v_add_f32_e32 v46, 1.0, v46
	v_rcp_f32_e32 v230, v230
	v_rcp_f32_e32 v46, v46
	v_mul_f32_e32 v229, v229, v230
	v_mul_f32_e32 v229, v46, v229
	v_cvt_pk_bf16_f32 v229, v229, v229
	global_store_short v67, v229, s[10:11] offset:2112
	s_waitcnt vmcnt(41)
	v_lshlrev_b32_e32 v232, 16, v232
	v_lshlrev_b32_e32 v233, 16, v233
	v_lshlrev_b32_e32 v70, 16, v70
	v_fmac_f32_e32 v233, v68, v232
	v_add_f32_e32 v232, v233, v70
	v_mul_f32_e32 v233, 0x3d372713, v232
	v_mul_f32_e32 v233, v232, v233
	v_fma_f32 v233, v232, v233, v232
	v_mul_f32_e32 v233, 0xbfcc422a, v233
	v_mul_f32_e32 v233, 0x3fb8aa3b, v233
	v_exp_f32_e32 v233, v233
	v_mul_f32_e32 v63, 0xbfb8aa3b, v63
	v_exp_f32_e32 v63, v63
	v_add_f32_e32 v233, 1.0, v233
	v_add_f32_e32 v63, 1.0, v63
	v_rcp_f32_e32 v233, v233
	v_rcp_f32_e32 v63, v63
	v_mul_f32_e32 v232, v232, v233
	v_mul_f32_e32 v232, v63, v232
	v_cvt_pk_bf16_f32 v232, v232, v232
	global_store_short v67, v232, s[10:11] offset:3072
	s_waitcnt vmcnt(39)
	v_lshlrev_b32_e32 v71, 16, v71
	v_lshlrev_b32_e32 v72, 16, v72
	v_lshlrev_b32_e32 v73, 16, v73
	v_fmac_f32_e32 v72, v69, v71
	v_add_f32_e32 v71, v72, v73
	v_mul_f32_e32 v72, 0x3d372713, v71
	v_mul_f32_e32 v72, v71, v72
	v_fma_f32 v72, v71, v72, v71
	v_mul_f32_e32 v72, 0xbfcc422a, v72
	v_mul_f32_e32 v72, 0x3fb8aa3b, v72
	v_exp_f32_e32 v72, v72
	v_mul_f32_e32 v47, 0xbfb8aa3b, v47
	v_exp_f32_e32 v47, v47
	v_add_f32_e32 v72, 1.0, v72
	v_add_f32_e32 v47, 1.0, v47
	v_rcp_f32_e32 v72, v72
	v_rcp_f32_e32 v47, v47
	v_mul_f32_e32 v71, v71, v72
	v_mul_f32_e32 v71, v47, v71
	v_cvt_pk_bf16_f32 v71, v71, v71
	global_store_short v67, v71, s[10:11] offset:3136
	v_add_u32_e32 v67, 0xa000, v65
	global_load_ushort v214, v67, s[0:1]
	global_load_ushort v215, v67, s[4:5]
	global_load_ushort v216, v67, s[6:7]
	global_load_ushort v217, v67, s[0:1] offset:64
	global_load_ushort v218, v67, s[4:5] offset:64
	global_load_ushort v219, v67, s[6:7] offset:64
	global_load_ushort v220, v67, s[0:1] offset:1024
	global_load_ushort v221, v67, s[4:5] offset:1024
	global_load_ushort v222, v67, s[6:7] offset:1024
	global_load_ushort v223, v67, s[0:1] offset:1088
	global_load_ushort v224, v67, s[4:5] offset:1088
	global_load_ushort v225, v67, s[6:7] offset:1088
	global_load_ushort v226, v67, s[0:1] offset:2048
	global_load_ushort v227, v67, s[4:5] offset:2048
	global_load_ushort v228, v67, s[6:7] offset:2048
	global_load_ushort v229, v67, s[0:1] offset:2112
	global_load_ushort v230, v67, s[4:5] offset:2112
	global_load_ushort v231, v67, s[6:7] offset:2112
	global_load_ushort v232, v67, s[0:1] offset:3072
	global_load_ushort v233, v67, s[4:5] offset:3072
	global_load_ushort v70, v67, s[6:7] offset:3072
	global_load_ushort v71, v67, s[0:1] offset:3136
	global_load_ushort v72, v67, s[4:5] offset:3136
	global_load_ushort v73, v67, s[6:7] offset:3136
	s_waitcnt vmcnt(53)
	v_lshlrev_b32_e32 v190, 16, v190
	v_lshlrev_b32_e32 v191, 16, v191
	v_lshlrev_b32_e32 v192, 16, v192
	v_fmac_f32_e32 v191, v68, v190
	v_add_f32_e32 v190, v191, v192
	v_mul_f32_e32 v191, 0x3d372713, v190
	v_mul_f32_e32 v191, v190, v191
	v_fma_f32 v191, v190, v191, v190
	v_mul_f32_e32 v191, 0xbfcc422a, v191
	v_mul_f32_e32 v191, 0x3fb8aa3b, v191
	v_exp_f32_e32 v191, v191
	v_mul_f32_e32 v16, 0xbfb8aa3b, v16
	v_exp_f32_e32 v16, v16
	v_add_f32_e32 v191, 1.0, v191
	v_add_f32_e32 v16, 1.0, v16
	v_rcp_f32_e32 v191, v191
	v_rcp_f32_e32 v16, v16
	v_mul_f32_e32 v190, v190, v191
	v_mul_f32_e32 v190, v16, v190
	v_cvt_pk_bf16_f32 v190, v190, v190
	global_store_short v66, v190, s[10:11]
	s_waitcnt vmcnt(51)
	v_lshlrev_b32_e32 v193, 16, v193
	v_lshlrev_b32_e32 v194, 16, v194
	v_lshlrev_b32_e32 v195, 16, v195
	v_fmac_f32_e32 v194, v69, v193
	v_add_f32_e32 v193, v194, v195
	v_mul_f32_e32 v194, 0x3d372713, v193
	v_mul_f32_e32 v194, v193, v194
	v_fma_f32 v194, v193, v194, v193
	v_mul_f32_e32 v194, 0xbfcc422a, v194
	v_mul_f32_e32 v194, 0x3fb8aa3b, v194
	v_exp_f32_e32 v194, v194
	v_mul_f32_e32 v0, 0xbfb8aa3b, v0
	v_exp_f32_e32 v0, v0
	v_add_f32_e32 v194, 1.0, v194
	v_add_f32_e32 v0, 1.0, v0
	v_rcp_f32_e32 v194, v194
	v_rcp_f32_e32 v0, v0
	v_mul_f32_e32 v193, v193, v194
	v_mul_f32_e32 v193, v0, v193
	v_cvt_pk_bf16_f32 v193, v193, v193
	global_store_short v66, v193, s[10:11] offset:64
	s_waitcnt vmcnt(49)
	v_lshlrev_b32_e32 v196, 16, v196
	v_lshlrev_b32_e32 v197, 16, v197
	v_lshlrev_b32_e32 v198, 16, v198
	v_fmac_f32_e32 v197, v68, v196
	v_add_f32_e32 v196, v197, v198
	v_mul_f32_e32 v197, 0x3d372713, v196
	v_mul_f32_e32 v197, v196, v197
	v_fma_f32 v197, v196, v197, v196
	v_mul_f32_e32 v197, 0xbfcc422a, v197
	v_mul_f32_e32 v197, 0x3fb8aa3b, v197
	v_exp_f32_e32 v197, v197
	v_mul_f32_e32 v17, 0xbfb8aa3b, v17
	v_exp_f32_e32 v17, v17
	v_add_f32_e32 v197, 1.0, v197
	v_add_f32_e32 v17, 1.0, v17
	v_rcp_f32_e32 v197, v197
	v_rcp_f32_e32 v17, v17
	v_mul_f32_e32 v196, v196, v197
	v_mul_f32_e32 v196, v17, v196
	v_cvt_pk_bf16_f32 v196, v196, v196
	global_store_short v66, v196, s[10:11] offset:1024
	s_waitcnt vmcnt(47)
	v_lshlrev_b32_e32 v199, 16, v199
	v_lshlrev_b32_e32 v200, 16, v200
	v_lshlrev_b32_e32 v201, 16, v201
	v_fmac_f32_e32 v200, v69, v199
	v_add_f32_e32 v199, v200, v201
	v_mul_f32_e32 v200, 0x3d372713, v199
	v_mul_f32_e32 v200, v199, v200
	v_fma_f32 v200, v199, v200, v199
	v_mul_f32_e32 v200, 0xbfcc422a, v200
	v_mul_f32_e32 v200, 0x3fb8aa3b, v200
	v_exp_f32_e32 v200, v200
	v_mul_f32_e32 v1, 0xbfb8aa3b, v1
	v_exp_f32_e32 v1, v1
	v_add_f32_e32 v200, 1.0, v200
	v_add_f32_e32 v1, 1.0, v1
	v_rcp_f32_e32 v200, v200
	v_rcp_f32_e32 v1, v1
	v_mul_f32_e32 v199, v199, v200
	v_mul_f32_e32 v199, v1, v199
	v_cvt_pk_bf16_f32 v199, v199, v199
	global_store_short v66, v199, s[10:11] offset:1088
	s_waitcnt vmcnt(45)
	v_lshlrev_b32_e32 v202, 16, v202
	v_lshlrev_b32_e32 v203, 16, v203
	v_lshlrev_b32_e32 v204, 16, v204
	v_fmac_f32_e32 v203, v68, v202
	v_add_f32_e32 v202, v203, v204
	v_mul_f32_e32 v203, 0x3d372713, v202
	v_mul_f32_e32 v203, v202, v203
	v_fma_f32 v203, v202, v203, v202
	v_mul_f32_e32 v203, 0xbfcc422a, v203
	v_mul_f32_e32 v203, 0x3fb8aa3b, v203
	v_exp_f32_e32 v203, v203
	v_mul_f32_e32 v18, 0xbfb8aa3b, v18
	v_exp_f32_e32 v18, v18
	v_add_f32_e32 v203, 1.0, v203
	v_add_f32_e32 v18, 1.0, v18
	v_rcp_f32_e32 v203, v203
	v_rcp_f32_e32 v18, v18
	v_mul_f32_e32 v202, v202, v203
	v_mul_f32_e32 v202, v18, v202
	v_cvt_pk_bf16_f32 v202, v202, v202
	global_store_short v66, v202, s[10:11] offset:2048
	s_waitcnt vmcnt(43)
	v_lshlrev_b32_e32 v205, 16, v205
	v_lshlrev_b32_e32 v206, 16, v206
	v_lshlrev_b32_e32 v207, 16, v207
	v_fmac_f32_e32 v206, v69, v205
	v_add_f32_e32 v205, v206, v207
	v_mul_f32_e32 v206, 0x3d372713, v205
	v_mul_f32_e32 v206, v205, v206
	v_fma_f32 v206, v205, v206, v205
	v_mul_f32_e32 v206, 0xbfcc422a, v206
	v_mul_f32_e32 v206, 0x3fb8aa3b, v206
	v_exp_f32_e32 v206, v206
	v_mul_f32_e32 v2, 0xbfb8aa3b, v2
	v_exp_f32_e32 v2, v2
	v_add_f32_e32 v206, 1.0, v206
	v_add_f32_e32 v2, 1.0, v2
	v_rcp_f32_e32 v206, v206
	v_rcp_f32_e32 v2, v2
	v_mul_f32_e32 v205, v205, v206
	v_mul_f32_e32 v205, v2, v205
	v_cvt_pk_bf16_f32 v205, v205, v205
	global_store_short v66, v205, s[10:11] offset:2112
	s_waitcnt vmcnt(41)
	v_lshlrev_b32_e32 v208, 16, v208
	v_lshlrev_b32_e32 v209, 16, v209
	v_lshlrev_b32_e32 v210, 16, v210
	v_fmac_f32_e32 v209, v68, v208
	v_add_f32_e32 v208, v209, v210
	v_mul_f32_e32 v209, 0x3d372713, v208
	v_mul_f32_e32 v209, v208, v209
	v_fma_f32 v209, v208, v209, v208
	v_mul_f32_e32 v209, 0xbfcc422a, v209
	v_mul_f32_e32 v209, 0x3fb8aa3b, v209
	v_exp_f32_e32 v209, v209
	v_mul_f32_e32 v19, 0xbfb8aa3b, v19
	v_exp_f32_e32 v19, v19
	v_add_f32_e32 v209, 1.0, v209
	v_add_f32_e32 v19, 1.0, v19
	v_rcp_f32_e32 v209, v209
	v_rcp_f32_e32 v19, v19
	v_mul_f32_e32 v208, v208, v209
	v_mul_f32_e32 v208, v19, v208
	v_cvt_pk_bf16_f32 v208, v208, v208
	global_store_short v66, v208, s[10:11] offset:3072
	s_waitcnt vmcnt(39)
	v_lshlrev_b32_e32 v211, 16, v211
	v_lshlrev_b32_e32 v212, 16, v212
	v_lshlrev_b32_e32 v213, 16, v213
	v_fmac_f32_e32 v212, v69, v211
	v_add_f32_e32 v211, v212, v213
	v_mul_f32_e32 v212, 0x3d372713, v211
	v_mul_f32_e32 v212, v211, v212
	v_fma_f32 v212, v211, v212, v211
	v_mul_f32_e32 v212, 0xbfcc422a, v212
	v_mul_f32_e32 v212, 0x3fb8aa3b, v212
	v_exp_f32_e32 v212, v212
	v_mul_f32_e32 v3, 0xbfb8aa3b, v3
	v_exp_f32_e32 v3, v3
	v_add_f32_e32 v212, 1.0, v212
	v_add_f32_e32 v3, 1.0, v3
	v_rcp_f32_e32 v212, v212
	v_rcp_f32_e32 v3, v3
	v_mul_f32_e32 v211, v211, v212
	v_mul_f32_e32 v211, v3, v211
	v_cvt_pk_bf16_f32 v211, v211, v211
	global_store_short v66, v211, s[10:11] offset:3136
	v_add_u32_e32 v66, 0xc000, v65
	global_load_ushort v190, v66, s[0:1]
	global_load_ushort v191, v66, s[4:5]
	global_load_ushort v192, v66, s[6:7]
	global_load_ushort v193, v66, s[0:1] offset:64
	global_load_ushort v194, v66, s[4:5] offset:64
	global_load_ushort v195, v66, s[6:7] offset:64
	global_load_ushort v196, v66, s[0:1] offset:1024
	global_load_ushort v197, v66, s[4:5] offset:1024
	global_load_ushort v198, v66, s[6:7] offset:1024
	global_load_ushort v199, v66, s[0:1] offset:1088
	global_load_ushort v200, v66, s[4:5] offset:1088
	global_load_ushort v201, v66, s[6:7] offset:1088
	global_load_ushort v202, v66, s[0:1] offset:2048
	global_load_ushort v203, v66, s[4:5] offset:2048
	global_load_ushort v204, v66, s[6:7] offset:2048
	global_load_ushort v205, v66, s[0:1] offset:2112
	global_load_ushort v206, v66, s[4:5] offset:2112
	global_load_ushort v207, v66, s[6:7] offset:2112
	global_load_ushort v208, v66, s[0:1] offset:3072
	global_load_ushort v209, v66, s[4:5] offset:3072
	global_load_ushort v210, v66, s[6:7] offset:3072
	global_load_ushort v211, v66, s[0:1] offset:3136
	global_load_ushort v212, v66, s[4:5] offset:3136
	global_load_ushort v213, v66, s[6:7] offset:3136
	s_waitcnt vmcnt(53)
	v_lshlrev_b32_e32 v214, 16, v214
	v_lshlrev_b32_e32 v215, 16, v215
	v_lshlrev_b32_e32 v216, 16, v216
	v_fmac_f32_e32 v215, v68, v214
	v_add_f32_e32 v214, v215, v216
	v_mul_f32_e32 v215, 0x3d372713, v214
	v_mul_f32_e32 v215, v214, v215
	v_fma_f32 v215, v214, v215, v214
	v_mul_f32_e32 v215, 0xbfcc422a, v215
	v_mul_f32_e32 v215, 0x3fb8aa3b, v215
	v_exp_f32_e32 v215, v215
	v_mul_f32_e32 v20, 0xbfb8aa3b, v20
	v_exp_f32_e32 v20, v20
	v_add_f32_e32 v215, 1.0, v215
	v_add_f32_e32 v20, 1.0, v20
	v_rcp_f32_e32 v215, v215
	v_rcp_f32_e32 v20, v20
	v_mul_f32_e32 v214, v214, v215
	v_mul_f32_e32 v214, v20, v214
	v_cvt_pk_bf16_f32 v214, v214, v214
	global_store_short v67, v214, s[10:11]
	s_waitcnt vmcnt(51)
	v_lshlrev_b32_e32 v217, 16, v217
	v_lshlrev_b32_e32 v218, 16, v218
	v_lshlrev_b32_e32 v219, 16, v219
	v_fmac_f32_e32 v218, v69, v217
	v_add_f32_e32 v217, v218, v219
	v_mul_f32_e32 v218, 0x3d372713, v217
	v_mul_f32_e32 v218, v217, v218
	v_fma_f32 v218, v217, v218, v217
	v_mul_f32_e32 v218, 0xbfcc422a, v218
	v_mul_f32_e32 v218, 0x3fb8aa3b, v218
	v_exp_f32_e32 v218, v218
	v_mul_f32_e32 v4, 0xbfb8aa3b, v4
	v_exp_f32_e32 v4, v4
	v_add_f32_e32 v218, 1.0, v218
	v_add_f32_e32 v4, 1.0, v4
	v_rcp_f32_e32 v218, v218
	v_rcp_f32_e32 v4, v4
	v_mul_f32_e32 v217, v217, v218
	v_mul_f32_e32 v217, v4, v217
	v_cvt_pk_bf16_f32 v217, v217, v217
	global_store_short v67, v217, s[10:11] offset:64
	s_waitcnt vmcnt(49)
	v_lshlrev_b32_e32 v220, 16, v220
	v_lshlrev_b32_e32 v221, 16, v221
	v_lshlrev_b32_e32 v222, 16, v222
	v_fmac_f32_e32 v221, v68, v220
	v_add_f32_e32 v220, v221, v222
	v_mul_f32_e32 v221, 0x3d372713, v220
	v_mul_f32_e32 v221, v220, v221
	v_fma_f32 v221, v220, v221, v220
	v_mul_f32_e32 v221, 0xbfcc422a, v221
	v_mul_f32_e32 v221, 0x3fb8aa3b, v221
	v_exp_f32_e32 v221, v221
	v_mul_f32_e32 v21, 0xbfb8aa3b, v21
	v_exp_f32_e32 v21, v21
	v_add_f32_e32 v221, 1.0, v221
	v_add_f32_e32 v21, 1.0, v21
	v_rcp_f32_e32 v221, v221
	v_rcp_f32_e32 v21, v21
	v_mul_f32_e32 v220, v220, v221
	v_mul_f32_e32 v220, v21, v220
	v_cvt_pk_bf16_f32 v220, v220, v220
	global_store_short v67, v220, s[10:11] offset:1024
	s_waitcnt vmcnt(47)
	v_lshlrev_b32_e32 v223, 16, v223
	v_lshlrev_b32_e32 v224, 16, v224
	v_lshlrev_b32_e32 v225, 16, v225
	v_fmac_f32_e32 v224, v69, v223
	v_add_f32_e32 v223, v224, v225
	v_mul_f32_e32 v224, 0x3d372713, v223
	v_mul_f32_e32 v224, v223, v224
	v_fma_f32 v224, v223, v224, v223
	v_mul_f32_e32 v224, 0xbfcc422a, v224
	v_mul_f32_e32 v224, 0x3fb8aa3b, v224
	v_exp_f32_e32 v224, v224
	v_mul_f32_e32 v5, 0xbfb8aa3b, v5
	v_exp_f32_e32 v5, v5
	v_add_f32_e32 v224, 1.0, v224
	v_add_f32_e32 v5, 1.0, v5
	v_rcp_f32_e32 v224, v224
	v_rcp_f32_e32 v5, v5
	v_mul_f32_e32 v223, v223, v224
	v_mul_f32_e32 v223, v5, v223
	v_cvt_pk_bf16_f32 v223, v223, v223
	global_store_short v67, v223, s[10:11] offset:1088
	s_waitcnt vmcnt(45)
	v_lshlrev_b32_e32 v226, 16, v226
	v_lshlrev_b32_e32 v227, 16, v227
	v_lshlrev_b32_e32 v228, 16, v228
	v_fmac_f32_e32 v227, v68, v226
	v_add_f32_e32 v226, v227, v228
	v_mul_f32_e32 v227, 0x3d372713, v226
	v_mul_f32_e32 v227, v226, v227
	v_fma_f32 v227, v226, v227, v226
	v_mul_f32_e32 v227, 0xbfcc422a, v227
	v_mul_f32_e32 v227, 0x3fb8aa3b, v227
	v_exp_f32_e32 v227, v227
	v_mul_f32_e32 v22, 0xbfb8aa3b, v22
	v_exp_f32_e32 v22, v22
	v_add_f32_e32 v227, 1.0, v227
	v_add_f32_e32 v22, 1.0, v22
	v_rcp_f32_e32 v227, v227
	v_rcp_f32_e32 v22, v22
	v_mul_f32_e32 v226, v226, v227
	v_mul_f32_e32 v226, v22, v226
	v_cvt_pk_bf16_f32 v226, v226, v226
	global_store_short v67, v226, s[10:11] offset:2048
	s_waitcnt vmcnt(43)
	v_lshlrev_b32_e32 v229, 16, v229
	v_lshlrev_b32_e32 v230, 16, v230
	v_lshlrev_b32_e32 v231, 16, v231
	v_fmac_f32_e32 v230, v69, v229
	v_add_f32_e32 v229, v230, v231
	v_mul_f32_e32 v230, 0x3d372713, v229
	v_mul_f32_e32 v230, v229, v230
	v_fma_f32 v230, v229, v230, v229
	v_mul_f32_e32 v230, 0xbfcc422a, v230
	v_mul_f32_e32 v230, 0x3fb8aa3b, v230
	v_exp_f32_e32 v230, v230
	v_mul_f32_e32 v6, 0xbfb8aa3b, v6
	v_exp_f32_e32 v6, v6
	v_add_f32_e32 v230, 1.0, v230
	v_add_f32_e32 v6, 1.0, v6
	v_rcp_f32_e32 v230, v230
	v_rcp_f32_e32 v6, v6
	v_mul_f32_e32 v229, v229, v230
	v_mul_f32_e32 v229, v6, v229
	v_cvt_pk_bf16_f32 v229, v229, v229
	global_store_short v67, v229, s[10:11] offset:2112
	s_waitcnt vmcnt(41)
	v_lshlrev_b32_e32 v232, 16, v232
	v_lshlrev_b32_e32 v233, 16, v233
	v_lshlrev_b32_e32 v70, 16, v70
	v_fmac_f32_e32 v233, v68, v232
	v_add_f32_e32 v232, v233, v70
	v_mul_f32_e32 v233, 0x3d372713, v232
	v_mul_f32_e32 v233, v232, v233
	v_fma_f32 v233, v232, v233, v232
	v_mul_f32_e32 v233, 0xbfcc422a, v233
	v_mul_f32_e32 v233, 0x3fb8aa3b, v233
	v_exp_f32_e32 v233, v233
	v_mul_f32_e32 v23, 0xbfb8aa3b, v23
	v_exp_f32_e32 v23, v23
	v_add_f32_e32 v233, 1.0, v233
	v_add_f32_e32 v23, 1.0, v23
	v_rcp_f32_e32 v233, v233
	v_rcp_f32_e32 v23, v23
	v_mul_f32_e32 v232, v232, v233
	v_mul_f32_e32 v232, v23, v232
	v_cvt_pk_bf16_f32 v232, v232, v232
	global_store_short v67, v232, s[10:11] offset:3072
	s_waitcnt vmcnt(39)
	v_lshlrev_b32_e32 v71, 16, v71
	v_lshlrev_b32_e32 v72, 16, v72
	v_lshlrev_b32_e32 v73, 16, v73
	v_fmac_f32_e32 v72, v69, v71
	v_add_f32_e32 v71, v72, v73
	v_mul_f32_e32 v72, 0x3d372713, v71
	v_mul_f32_e32 v72, v71, v72
	v_fma_f32 v72, v71, v72, v71
	v_mul_f32_e32 v72, 0xbfcc422a, v72
	v_mul_f32_e32 v72, 0x3fb8aa3b, v72
	v_exp_f32_e32 v72, v72
	v_mul_f32_e32 v7, 0xbfb8aa3b, v7
	v_exp_f32_e32 v7, v7
	v_add_f32_e32 v72, 1.0, v72
	v_add_f32_e32 v7, 1.0, v7
	v_rcp_f32_e32 v72, v72
	v_rcp_f32_e32 v7, v7
	v_mul_f32_e32 v71, v71, v72
	v_mul_f32_e32 v71, v7, v71
	v_cvt_pk_bf16_f32 v71, v71, v71
	global_store_short v67, v71, s[10:11] offset:3136
	v_add_u32_e32 v67, 0xe000, v65
	global_load_ushort v214, v67, s[0:1]
	global_load_ushort v215, v67, s[4:5]
	global_load_ushort v216, v67, s[6:7]
	global_load_ushort v217, v67, s[0:1] offset:64
	global_load_ushort v218, v67, s[4:5] offset:64
	global_load_ushort v219, v67, s[6:7] offset:64
	global_load_ushort v220, v67, s[0:1] offset:1024
	global_load_ushort v221, v67, s[4:5] offset:1024
	global_load_ushort v222, v67, s[6:7] offset:1024
	global_load_ushort v223, v67, s[0:1] offset:1088
	global_load_ushort v224, v67, s[4:5] offset:1088
	global_load_ushort v225, v67, s[6:7] offset:1088
	global_load_ushort v226, v67, s[0:1] offset:2048
	global_load_ushort v227, v67, s[4:5] offset:2048
	global_load_ushort v228, v67, s[6:7] offset:2048
	global_load_ushort v229, v67, s[0:1] offset:2112
	global_load_ushort v230, v67, s[4:5] offset:2112
	global_load_ushort v231, v67, s[6:7] offset:2112
	global_load_ushort v232, v67, s[0:1] offset:3072
	global_load_ushort v233, v67, s[4:5] offset:3072
	global_load_ushort v70, v67, s[6:7] offset:3072
	global_load_ushort v71, v67, s[0:1] offset:3136
	global_load_ushort v72, v67, s[4:5] offset:3136
	global_load_ushort v73, v67, s[6:7] offset:3136
	s_waitcnt vmcnt(53)
	v_lshlrev_b32_e32 v190, 16, v190
	v_lshlrev_b32_e32 v191, 16, v191
	v_lshlrev_b32_e32 v192, 16, v192
	v_fmac_f32_e32 v191, v68, v190
	v_add_f32_e32 v190, v191, v192
	v_mul_f32_e32 v191, 0x3d372713, v190
	v_mul_f32_e32 v191, v190, v191
	v_fma_f32 v191, v190, v191, v190
	v_mul_f32_e32 v191, 0xbfcc422a, v191
	v_mul_f32_e32 v191, 0x3fb8aa3b, v191
	v_exp_f32_e32 v191, v191
	v_mul_f32_e32 v24, 0xbfb8aa3b, v24
	v_exp_f32_e32 v24, v24
	v_add_f32_e32 v191, 1.0, v191
	v_add_f32_e32 v24, 1.0, v24
	v_rcp_f32_e32 v191, v191
	v_rcp_f32_e32 v24, v24
	v_mul_f32_e32 v190, v190, v191
	v_mul_f32_e32 v190, v24, v190
	v_cvt_pk_bf16_f32 v190, v190, v190
	global_store_short v66, v190, s[10:11]
	s_waitcnt vmcnt(51)
	v_lshlrev_b32_e32 v193, 16, v193
	v_lshlrev_b32_e32 v194, 16, v194
	v_lshlrev_b32_e32 v195, 16, v195
	v_fmac_f32_e32 v194, v69, v193
	v_add_f32_e32 v193, v194, v195
	v_mul_f32_e32 v194, 0x3d372713, v193
	v_mul_f32_e32 v194, v193, v194
	v_fma_f32 v194, v193, v194, v193
	v_mul_f32_e32 v194, 0xbfcc422a, v194
	v_mul_f32_e32 v194, 0x3fb8aa3b, v194
	v_exp_f32_e32 v194, v194
	v_mul_f32_e32 v8, 0xbfb8aa3b, v8
	v_exp_f32_e32 v8, v8
	v_add_f32_e32 v194, 1.0, v194
	v_add_f32_e32 v8, 1.0, v8
	v_rcp_f32_e32 v194, v194
	v_rcp_f32_e32 v8, v8
	v_mul_f32_e32 v193, v193, v194
	v_mul_f32_e32 v193, v8, v193
	v_cvt_pk_bf16_f32 v193, v193, v193
	global_store_short v66, v193, s[10:11] offset:64
	s_waitcnt vmcnt(49)
	v_lshlrev_b32_e32 v196, 16, v196
	v_lshlrev_b32_e32 v197, 16, v197
	v_lshlrev_b32_e32 v198, 16, v198
	v_fmac_f32_e32 v197, v68, v196
	v_add_f32_e32 v196, v197, v198
	v_mul_f32_e32 v197, 0x3d372713, v196
	v_mul_f32_e32 v197, v196, v197
	v_fma_f32 v197, v196, v197, v196
	v_mul_f32_e32 v197, 0xbfcc422a, v197
	v_mul_f32_e32 v197, 0x3fb8aa3b, v197
	v_exp_f32_e32 v197, v197
	v_mul_f32_e32 v25, 0xbfb8aa3b, v25
	v_exp_f32_e32 v25, v25
	v_add_f32_e32 v197, 1.0, v197
	v_add_f32_e32 v25, 1.0, v25
	v_rcp_f32_e32 v197, v197
	v_rcp_f32_e32 v25, v25
	v_mul_f32_e32 v196, v196, v197
	v_mul_f32_e32 v196, v25, v196
	v_cvt_pk_bf16_f32 v196, v196, v196
	global_store_short v66, v196, s[10:11] offset:1024
	s_waitcnt vmcnt(47)
	v_lshlrev_b32_e32 v199, 16, v199
	v_lshlrev_b32_e32 v200, 16, v200
	v_lshlrev_b32_e32 v201, 16, v201
	v_fmac_f32_e32 v200, v69, v199
	v_add_f32_e32 v199, v200, v201
	v_mul_f32_e32 v200, 0x3d372713, v199
	v_mul_f32_e32 v200, v199, v200
	v_fma_f32 v200, v199, v200, v199
	v_mul_f32_e32 v200, 0xbfcc422a, v200
	v_mul_f32_e32 v200, 0x3fb8aa3b, v200
	v_exp_f32_e32 v200, v200
	v_mul_f32_e32 v9, 0xbfb8aa3b, v9
	v_exp_f32_e32 v9, v9
	v_add_f32_e32 v200, 1.0, v200
	v_add_f32_e32 v9, 1.0, v9
	v_rcp_f32_e32 v200, v200
	v_rcp_f32_e32 v9, v9
	v_mul_f32_e32 v199, v199, v200
	v_mul_f32_e32 v199, v9, v199
	v_cvt_pk_bf16_f32 v199, v199, v199
	global_store_short v66, v199, s[10:11] offset:1088
	s_waitcnt vmcnt(45)
	v_lshlrev_b32_e32 v202, 16, v202
	v_lshlrev_b32_e32 v203, 16, v203
	v_lshlrev_b32_e32 v204, 16, v204
	v_fmac_f32_e32 v203, v68, v202
	v_add_f32_e32 v202, v203, v204
	v_mul_f32_e32 v203, 0x3d372713, v202
	v_mul_f32_e32 v203, v202, v203
	v_fma_f32 v203, v202, v203, v202
	v_mul_f32_e32 v203, 0xbfcc422a, v203
	v_mul_f32_e32 v203, 0x3fb8aa3b, v203
	v_exp_f32_e32 v203, v203
	v_mul_f32_e32 v26, 0xbfb8aa3b, v26
	v_exp_f32_e32 v26, v26
	v_add_f32_e32 v203, 1.0, v203
	v_add_f32_e32 v26, 1.0, v26
	v_rcp_f32_e32 v203, v203
	v_rcp_f32_e32 v26, v26
	v_mul_f32_e32 v202, v202, v203
	v_mul_f32_e32 v202, v26, v202
	v_cvt_pk_bf16_f32 v202, v202, v202
	global_store_short v66, v202, s[10:11] offset:2048
	s_waitcnt vmcnt(43)
	v_lshlrev_b32_e32 v205, 16, v205
	v_lshlrev_b32_e32 v206, 16, v206
	v_lshlrev_b32_e32 v207, 16, v207
	v_fmac_f32_e32 v206, v69, v205
	v_add_f32_e32 v205, v206, v207
	v_mul_f32_e32 v206, 0x3d372713, v205
	v_mul_f32_e32 v206, v205, v206
	v_fma_f32 v206, v205, v206, v205
	v_mul_f32_e32 v206, 0xbfcc422a, v206
	v_mul_f32_e32 v206, 0x3fb8aa3b, v206
	v_exp_f32_e32 v206, v206
	v_mul_f32_e32 v10, 0xbfb8aa3b, v10
	v_exp_f32_e32 v10, v10
	v_add_f32_e32 v206, 1.0, v206
	v_add_f32_e32 v10, 1.0, v10
	v_rcp_f32_e32 v206, v206
	v_rcp_f32_e32 v10, v10
	v_mul_f32_e32 v205, v205, v206
	v_mul_f32_e32 v205, v10, v205
	v_cvt_pk_bf16_f32 v205, v205, v205
	global_store_short v66, v205, s[10:11] offset:2112
	s_waitcnt vmcnt(41)
	v_lshlrev_b32_e32 v208, 16, v208
	v_lshlrev_b32_e32 v209, 16, v209
	v_lshlrev_b32_e32 v210, 16, v210
	v_fmac_f32_e32 v209, v68, v208
	v_add_f32_e32 v208, v209, v210
	v_mul_f32_e32 v209, 0x3d372713, v208
	v_mul_f32_e32 v209, v208, v209
	v_fma_f32 v209, v208, v209, v208
	v_mul_f32_e32 v209, 0xbfcc422a, v209
	v_mul_f32_e32 v209, 0x3fb8aa3b, v209
	v_exp_f32_e32 v209, v209
	v_mul_f32_e32 v27, 0xbfb8aa3b, v27
	v_exp_f32_e32 v27, v27
	v_add_f32_e32 v209, 1.0, v209
	v_add_f32_e32 v27, 1.0, v27
	v_rcp_f32_e32 v209, v209
	v_rcp_f32_e32 v27, v27
	v_mul_f32_e32 v208, v208, v209
	v_mul_f32_e32 v208, v27, v208
	v_cvt_pk_bf16_f32 v208, v208, v208
	global_store_short v66, v208, s[10:11] offset:3072
	s_waitcnt vmcnt(39)
	v_lshlrev_b32_e32 v211, 16, v211
	v_lshlrev_b32_e32 v212, 16, v212
	v_lshlrev_b32_e32 v213, 16, v213
	v_fmac_f32_e32 v212, v69, v211
	v_add_f32_e32 v211, v212, v213
	v_mul_f32_e32 v212, 0x3d372713, v211
	v_mul_f32_e32 v212, v211, v212
	v_fma_f32 v212, v211, v212, v211
	v_mul_f32_e32 v212, 0xbfcc422a, v212
	v_mul_f32_e32 v212, 0x3fb8aa3b, v212
	v_exp_f32_e32 v212, v212
	v_mul_f32_e32 v11, 0xbfb8aa3b, v11
	v_exp_f32_e32 v11, v11
	v_add_f32_e32 v212, 1.0, v212
	v_add_f32_e32 v11, 1.0, v11
	v_rcp_f32_e32 v212, v212
	v_rcp_f32_e32 v11, v11
	v_mul_f32_e32 v211, v211, v212
	v_mul_f32_e32 v211, v11, v211
	v_cvt_pk_bf16_f32 v211, v211, v211
	global_store_short v66, v211, s[10:11] offset:3136
	s_waitcnt vmcnt(29)
	v_lshlrev_b32_e32 v214, 16, v214
	v_lshlrev_b32_e32 v215, 16, v215
	v_lshlrev_b32_e32 v216, 16, v216
	v_fmac_f32_e32 v215, v68, v214
	v_add_f32_e32 v214, v215, v216
	v_mul_f32_e32 v215, 0x3d372713, v214
	v_mul_f32_e32 v215, v214, v215
	v_fma_f32 v215, v214, v215, v214
	v_mul_f32_e32 v215, 0xbfcc422a, v215
	v_mul_f32_e32 v215, 0x3fb8aa3b, v215
	v_exp_f32_e32 v215, v215
	v_mul_f32_e32 v28, 0xbfb8aa3b, v28
	v_exp_f32_e32 v28, v28
	v_add_f32_e32 v215, 1.0, v215
	v_add_f32_e32 v28, 1.0, v28
	v_rcp_f32_e32 v215, v215
	v_rcp_f32_e32 v28, v28
	v_mul_f32_e32 v214, v214, v215
	v_mul_f32_e32 v214, v28, v214
	v_cvt_pk_bf16_f32 v214, v214, v214
	global_store_short v67, v214, s[10:11]
	s_waitcnt vmcnt(27)
	v_lshlrev_b32_e32 v217, 16, v217
	v_lshlrev_b32_e32 v218, 16, v218
	v_lshlrev_b32_e32 v219, 16, v219
	v_fmac_f32_e32 v218, v69, v217
	v_add_f32_e32 v217, v218, v219
	v_mul_f32_e32 v218, 0x3d372713, v217
	v_mul_f32_e32 v218, v217, v218
	v_fma_f32 v218, v217, v218, v217
	v_mul_f32_e32 v218, 0xbfcc422a, v218
	v_mul_f32_e32 v218, 0x3fb8aa3b, v218
	v_exp_f32_e32 v218, v218
	v_mul_f32_e32 v12, 0xbfb8aa3b, v12
	v_exp_f32_e32 v12, v12
	v_add_f32_e32 v218, 1.0, v218
	v_add_f32_e32 v12, 1.0, v12
	v_rcp_f32_e32 v218, v218
	v_rcp_f32_e32 v12, v12
	v_mul_f32_e32 v217, v217, v218
	v_mul_f32_e32 v217, v12, v217
	v_cvt_pk_bf16_f32 v217, v217, v217
	global_store_short v67, v217, s[10:11] offset:64
	s_waitcnt vmcnt(25)
	v_lshlrev_b32_e32 v220, 16, v220
	v_lshlrev_b32_e32 v221, 16, v221
	v_lshlrev_b32_e32 v222, 16, v222
	v_fmac_f32_e32 v221, v68, v220
	v_add_f32_e32 v220, v221, v222
	v_mul_f32_e32 v221, 0x3d372713, v220
	v_mul_f32_e32 v221, v220, v221
	v_fma_f32 v221, v220, v221, v220
	v_mul_f32_e32 v221, 0xbfcc422a, v221
	v_mul_f32_e32 v221, 0x3fb8aa3b, v221
	v_exp_f32_e32 v221, v221
	v_mul_f32_e32 v29, 0xbfb8aa3b, v29
	v_exp_f32_e32 v29, v29
	v_add_f32_e32 v221, 1.0, v221
	v_add_f32_e32 v29, 1.0, v29
	v_rcp_f32_e32 v221, v221
	v_rcp_f32_e32 v29, v29
	v_mul_f32_e32 v220, v220, v221
	v_mul_f32_e32 v220, v29, v220
	v_cvt_pk_bf16_f32 v220, v220, v220
	global_store_short v67, v220, s[10:11] offset:1024
	s_waitcnt vmcnt(23)
	v_lshlrev_b32_e32 v223, 16, v223
	v_lshlrev_b32_e32 v224, 16, v224
	v_lshlrev_b32_e32 v225, 16, v225
	v_fmac_f32_e32 v224, v69, v223
	v_add_f32_e32 v223, v224, v225
	v_mul_f32_e32 v224, 0x3d372713, v223
	v_mul_f32_e32 v224, v223, v224
	v_fma_f32 v224, v223, v224, v223
	v_mul_f32_e32 v224, 0xbfcc422a, v224
	v_mul_f32_e32 v224, 0x3fb8aa3b, v224
	v_exp_f32_e32 v224, v224
	v_mul_f32_e32 v13, 0xbfb8aa3b, v13
	v_exp_f32_e32 v13, v13
	v_add_f32_e32 v224, 1.0, v224
	v_add_f32_e32 v13, 1.0, v13
	v_rcp_f32_e32 v224, v224
	v_rcp_f32_e32 v13, v13
	v_mul_f32_e32 v223, v223, v224
	v_mul_f32_e32 v223, v13, v223
	v_cvt_pk_bf16_f32 v223, v223, v223
	global_store_short v67, v223, s[10:11] offset:1088
	s_waitcnt vmcnt(21)
	v_lshlrev_b32_e32 v226, 16, v226
	v_lshlrev_b32_e32 v227, 16, v227
	v_lshlrev_b32_e32 v228, 16, v228
	v_fmac_f32_e32 v227, v68, v226
	v_add_f32_e32 v226, v227, v228
	v_mul_f32_e32 v227, 0x3d372713, v226
	v_mul_f32_e32 v227, v226, v227
	v_fma_f32 v227, v226, v227, v226
	v_mul_f32_e32 v227, 0xbfcc422a, v227
	v_mul_f32_e32 v227, 0x3fb8aa3b, v227
	v_exp_f32_e32 v227, v227
	v_mul_f32_e32 v30, 0xbfb8aa3b, v30
	v_exp_f32_e32 v30, v30
	v_add_f32_e32 v227, 1.0, v227
	v_add_f32_e32 v30, 1.0, v30
	v_rcp_f32_e32 v227, v227
	v_rcp_f32_e32 v30, v30
	v_mul_f32_e32 v226, v226, v227
	v_mul_f32_e32 v226, v30, v226
	v_cvt_pk_bf16_f32 v226, v226, v226
	global_store_short v67, v226, s[10:11] offset:2048
	s_waitcnt vmcnt(19)
	v_lshlrev_b32_e32 v229, 16, v229
	v_lshlrev_b32_e32 v230, 16, v230
	v_lshlrev_b32_e32 v231, 16, v231
	v_fmac_f32_e32 v230, v69, v229
	v_add_f32_e32 v229, v230, v231
	v_mul_f32_e32 v230, 0x3d372713, v229
	v_mul_f32_e32 v230, v229, v230
	v_fma_f32 v230, v229, v230, v229
	v_mul_f32_e32 v230, 0xbfcc422a, v230
	v_mul_f32_e32 v230, 0x3fb8aa3b, v230
	v_exp_f32_e32 v230, v230
	v_mul_f32_e32 v14, 0xbfb8aa3b, v14
	v_exp_f32_e32 v14, v14
	v_add_f32_e32 v230, 1.0, v230
	v_add_f32_e32 v14, 1.0, v14
	v_rcp_f32_e32 v230, v230
	v_rcp_f32_e32 v14, v14
	v_mul_f32_e32 v229, v229, v230
	v_mul_f32_e32 v229, v14, v229
	v_cvt_pk_bf16_f32 v229, v229, v229
	global_store_short v67, v229, s[10:11] offset:2112
	s_waitcnt vmcnt(17)
	v_lshlrev_b32_e32 v232, 16, v232
	v_lshlrev_b32_e32 v233, 16, v233
	v_lshlrev_b32_e32 v70, 16, v70
	v_fmac_f32_e32 v233, v68, v232
	v_add_f32_e32 v232, v233, v70
	v_mul_f32_e32 v233, 0x3d372713, v232
	v_mul_f32_e32 v233, v232, v233
	v_fma_f32 v233, v232, v233, v232
	v_mul_f32_e32 v233, 0xbfcc422a, v233
	v_mul_f32_e32 v233, 0x3fb8aa3b, v233
	v_exp_f32_e32 v233, v233
	v_mul_f32_e32 v31, 0xbfb8aa3b, v31
	v_exp_f32_e32 v31, v31
	v_add_f32_e32 v233, 1.0, v233
	v_add_f32_e32 v31, 1.0, v31
	v_rcp_f32_e32 v233, v233
	v_rcp_f32_e32 v31, v31
	v_mul_f32_e32 v232, v232, v233
	v_mul_f32_e32 v232, v31, v232
	v_cvt_pk_bf16_f32 v232, v232, v232
	global_store_short v67, v232, s[10:11] offset:3072
	s_waitcnt vmcnt(15)
	v_lshlrev_b32_e32 v71, 16, v71
	v_lshlrev_b32_e32 v72, 16, v72
	v_lshlrev_b32_e32 v73, 16, v73
	v_fmac_f32_e32 v72, v69, v71
	v_add_f32_e32 v71, v72, v73
	v_mul_f32_e32 v72, 0x3d372713, v71
	v_mul_f32_e32 v72, v71, v72
	v_fma_f32 v72, v71, v72, v71
	v_mul_f32_e32 v72, 0xbfcc422a, v72
	v_mul_f32_e32 v72, 0x3fb8aa3b, v72
	v_exp_f32_e32 v72, v72
	v_mul_f32_e32 v15, 0xbfb8aa3b, v15
	v_exp_f32_e32 v15, v15
	v_add_f32_e32 v72, 1.0, v72
	v_add_f32_e32 v15, 1.0, v15
	v_rcp_f32_e32 v72, v72
	v_rcp_f32_e32 v15, v15
	v_mul_f32_e32 v71, v71, v72
	v_mul_f32_e32 v71, v15, v71
	v_cvt_pk_bf16_f32 v71, v71, v71
	global_store_short v67, v71, s[10:11] offset:3136
	s_add_i32 s40, s40, s20
	s_add_i32 s22, s22, s23
	s_add_i32 s24, s24, s25
	s_cmp_gt_i32 s40, 31
	v_readlane_b32 s45, v251, 24
	v_readlane_b32 s46, v251, 25
	v_readlane_b32 s47, v251, 26
	v_readlane_b32 s48, v251, 27
	v_readlane_b32 s49, v251, 28
	v_readlane_b32 s52, v251, 31
	v_readlane_b32 s53, v251, 32
	v_readlane_b32 s54, v251, 33
	v_readlane_b32 s55, v251, 34
	v_readlane_b32 s56, v251, 35
	v_readlane_b32 s57, v251, 36
	v_readlane_b32 s58, v251, 37
	v_readlane_b32 s59, v251, 38
	s_cbranch_scc1 .LBB0_1662

.LBB0_3643:
	s_waitcnt vmcnt(0)
	v_readlane_b32 s40, v251, 23
	v_readlane_b32 s42, v251, 25
	v_readlane_b32 s43, v251, 26
	v_readlane_b32 s46, v251, 29
	v_readlane_b32 s47, v251, 30
	s_mov_b64 s[42:43], s[46:47]
	v_ashrrev_i32_e32 v64, 1, v144
	v_and_b32_e32 v64, 0xffffffc0, v64
	v_add_u32_e32 v66, s2, v64
	v_lshrrev_b32_e32 v67, 3, v144
	v_and_b32_e32 v64, 0x5f, v144
	v_and_or_b32 v68, v67, 4, v66
	v_or_b32_e32 v64, s37, v64
	v_lshlrev_b32_e32 v65, 10, v68
	v_lshl_add_u32 v65, v64, 1, v65
	v_lshlrev_b32_e32 v74, 2, v64
	global_load_dword v68, v74, s[42:43] offset:2048
	global_load_dword v69, v74, s[42:43] offset:2176
	v_mov_b32_e32 v66, v65
	global_load_ushort v190, v66, s[0:1]
	global_load_ushort v191, v66, s[4:5]
	global_load_ushort v192, v66, s[6:7]
	global_load_ushort v193, v66, s[0:1] offset:64
	global_load_ushort v194, v66, s[4:5] offset:64
	global_load_ushort v195, v66, s[6:7] offset:64
	global_load_ushort v196, v66, s[0:1] offset:1024
	global_load_ushort v197, v66, s[4:5] offset:1024
	global_load_ushort v198, v66, s[6:7] offset:1024
	global_load_ushort v199, v66, s[0:1] offset:1088
	global_load_ushort v200, v66, s[4:5] offset:1088
	global_load_ushort v201, v66, s[6:7] offset:1088
	global_load_ushort v202, v66, s[0:1] offset:2048
	global_load_ushort v203, v66, s[4:5] offset:2048
	global_load_ushort v204, v66, s[6:7] offset:2048
	global_load_ushort v205, v66, s[0:1] offset:2112
	global_load_ushort v206, v66, s[4:5] offset:2112
	global_load_ushort v207, v66, s[6:7] offset:2112
	global_load_ushort v208, v66, s[0:1] offset:3072
	global_load_ushort v209, v66, s[4:5] offset:3072
	global_load_ushort v210, v66, s[6:7] offset:3072
	global_load_ushort v211, v66, s[0:1] offset:3136
	global_load_ushort v212, v66, s[4:5] offset:3136
	global_load_ushort v213, v66, s[6:7] offset:3136
	v_add_u32_e32 v67, 0x2000, v65
	global_load_ushort v214, v67, s[0:1]
	global_load_ushort v215, v67, s[4:5]
	global_load_ushort v216, v67, s[6:7]
	global_load_ushort v217, v67, s[0:1] offset:64
	global_load_ushort v218, v67, s[4:5] offset:64
	global_load_ushort v219, v67, s[6:7] offset:64
	global_load_ushort v220, v67, s[0:1] offset:1024
	global_load_ushort v221, v67, s[4:5] offset:1024
	global_load_ushort v222, v67, s[6:7] offset:1024
	global_load_ushort v223, v67, s[0:1] offset:1088
	global_load_ushort v224, v67, s[4:5] offset:1088
	global_load_ushort v225, v67, s[6:7] offset:1088
	global_load_ushort v226, v67, s[0:1] offset:2048
	global_load_ushort v227, v67, s[4:5] offset:2048
	global_load_ushort v228, v67, s[6:7] offset:2048
	global_load_ushort v229, v67, s[0:1] offset:2112
	global_load_ushort v230, v67, s[4:5] offset:2112
	global_load_ushort v231, v67, s[6:7] offset:2112
	global_load_ushort v232, v67, s[0:1] offset:3072
	global_load_ushort v233, v67, s[4:5] offset:3072
	global_load_ushort v70, v67, s[6:7] offset:3072
	global_load_ushort v71, v67, s[0:1] offset:3136
	global_load_ushort v72, v67, s[4:5] offset:3136
	global_load_ushort v73, v67, s[6:7] offset:3136
	s_waitcnt vmcnt(48)
	s_waitcnt vmcnt(45)
	v_lshlrev_b32_e32 v190, 16, v190
	v_lshlrev_b32_e32 v191, 16, v191
	v_lshlrev_b32_e32 v192, 16, v192
	v_fmac_f32_e32 v191, v68, v190
	v_add_f32_e32 v190, v191, v192
	v_mul_f32_e32 v191, 0x3d372713, v190
	v_mul_f32_e32 v191, v190, v191
	v_fma_f32 v191, v190, v191, v190
	v_mul_f32_e32 v191, 0xbfcc422a, v191
	v_mul_f32_e32 v191, 0x3fb8aa3b, v191
	v_exp_f32_e32 v191, v191
	v_mul_f32_e32 v48, 0xbfb8aa3b, v48
	v_exp_f32_e32 v48, v48
	v_add_f32_e32 v191, 1.0, v191
	v_add_f32_e32 v48, 1.0, v48
	v_rcp_f32_e32 v191, v191
	v_rcp_f32_e32 v48, v48
	v_mul_f32_e32 v190, v190, v191
	v_mul_f32_e32 v190, v48, v190
	v_cvt_pk_bf16_f32 v190, v190, v190
	global_store_short v66, v190, s[10:11]
	s_waitcnt vmcnt(43)
	v_lshlrev_b32_e32 v193, 16, v193
	v_lshlrev_b32_e32 v194, 16, v194
	v_lshlrev_b32_e32 v195, 16, v195
	v_fmac_f32_e32 v194, v69, v193
	v_add_f32_e32 v193, v194, v195
	v_mul_f32_e32 v194, 0x3d372713, v193
	v_mul_f32_e32 v194, v193, v194
	v_fma_f32 v194, v193, v194, v193
	v_mul_f32_e32 v194, 0xbfcc422a, v194
	v_mul_f32_e32 v194, 0x3fb8aa3b, v194
	v_exp_f32_e32 v194, v194
	v_mul_f32_e32 v32, 0xbfb8aa3b, v32
	v_exp_f32_e32 v32, v32
	v_add_f32_e32 v194, 1.0, v194
	v_add_f32_e32 v32, 1.0, v32
	v_rcp_f32_e32 v194, v194
	v_rcp_f32_e32 v32, v32
	v_mul_f32_e32 v193, v193, v194
	v_mul_f32_e32 v193, v32, v193
	v_cvt_pk_bf16_f32 v193, v193, v193
	global_store_short v66, v193, s[10:11] offset:64
	s_waitcnt vmcnt(41)
	v_lshlrev_b32_e32 v196, 16, v196
	v_lshlrev_b32_e32 v197, 16, v197
	v_lshlrev_b32_e32 v198, 16, v198
	v_fmac_f32_e32 v197, v68, v196
	v_add_f32_e32 v196, v197, v198
	v_mul_f32_e32 v197, 0x3d372713, v196
	v_mul_f32_e32 v197, v196, v197
	v_fma_f32 v197, v196, v197, v196
	v_mul_f32_e32 v197, 0xbfcc422a, v197
	v_mul_f32_e32 v197, 0x3fb8aa3b, v197
	v_exp_f32_e32 v197, v197
	v_mul_f32_e32 v49, 0xbfb8aa3b, v49
	v_exp_f32_e32 v49, v49
	v_add_f32_e32 v197, 1.0, v197
	v_add_f32_e32 v49, 1.0, v49
	v_rcp_f32_e32 v197, v197
	v_rcp_f32_e32 v49, v49
	v_mul_f32_e32 v196, v196, v197
	v_mul_f32_e32 v196, v49, v196
	v_cvt_pk_bf16_f32 v196, v196, v196
	global_store_short v66, v196, s[10:11] offset:1024
	s_waitcnt vmcnt(39)
	v_lshlrev_b32_e32 v199, 16, v199
	v_lshlrev_b32_e32 v200, 16, v200
	v_lshlrev_b32_e32 v201, 16, v201
	v_fmac_f32_e32 v200, v69, v199
	v_add_f32_e32 v199, v200, v201
	v_mul_f32_e32 v200, 0x3d372713, v199
	v_mul_f32_e32 v200, v199, v200
	v_fma_f32 v200, v199, v200, v199
	v_mul_f32_e32 v200, 0xbfcc422a, v200
	v_mul_f32_e32 v200, 0x3fb8aa3b, v200
	v_exp_f32_e32 v200, v200
	v_mul_f32_e32 v33, 0xbfb8aa3b, v33
	v_exp_f32_e32 v33, v33
	v_add_f32_e32 v200, 1.0, v200
	v_add_f32_e32 v33, 1.0, v33
	v_rcp_f32_e32 v200, v200
	v_rcp_f32_e32 v33, v33
	v_mul_f32_e32 v199, v199, v200
	v_mul_f32_e32 v199, v33, v199
	v_cvt_pk_bf16_f32 v199, v199, v199
	global_store_short v66, v199, s[10:11] offset:1088
	s_waitcnt vmcnt(37)
	v_lshlrev_b32_e32 v202, 16, v202
	v_lshlrev_b32_e32 v203, 16, v203
	v_lshlrev_b32_e32 v204, 16, v204
	v_fmac_f32_e32 v203, v68, v202
	v_add_f32_e32 v202, v203, v204
	v_mul_f32_e32 v203, 0x3d372713, v202
	v_mul_f32_e32 v203, v202, v203
	v_fma_f32 v203, v202, v203, v202
	v_mul_f32_e32 v203, 0xbfcc422a, v203
	v_mul_f32_e32 v203, 0x3fb8aa3b, v203
	v_exp_f32_e32 v203, v203
	v_mul_f32_e32 v50, 0xbfb8aa3b, v50
	v_exp_f32_e32 v50, v50
	v_add_f32_e32 v203, 1.0, v203
	v_add_f32_e32 v50, 1.0, v50
	v_rcp_f32_e32 v203, v203
	v_rcp_f32_e32 v50, v50
	v_mul_f32_e32 v202, v202, v203
	v_mul_f32_e32 v202, v50, v202
	v_cvt_pk_bf16_f32 v202, v202, v202
	global_store_short v66, v202, s[10:11] offset:2048
	s_waitcnt vmcnt(35)
	v_lshlrev_b32_e32 v205, 16, v205
	v_lshlrev_b32_e32 v206, 16, v206
	v_lshlrev_b32_e32 v207, 16, v207
	v_fmac_f32_e32 v206, v69, v205
	v_add_f32_e32 v205, v206, v207
	v_mul_f32_e32 v206, 0x3d372713, v205
	v_mul_f32_e32 v206, v205, v206
	v_fma_f32 v206, v205, v206, v205
	v_mul_f32_e32 v206, 0xbfcc422a, v206
	v_mul_f32_e32 v206, 0x3fb8aa3b, v206
	v_exp_f32_e32 v206, v206
	v_mul_f32_e32 v34, 0xbfb8aa3b, v34
	v_exp_f32_e32 v34, v34
	v_add_f32_e32 v206, 1.0, v206
	v_add_f32_e32 v34, 1.0, v34
	v_rcp_f32_e32 v206, v206
	v_rcp_f32_e32 v34, v34
	v_mul_f32_e32 v205, v205, v206
	v_mul_f32_e32 v205, v34, v205
	v_cvt_pk_bf16_f32 v205, v205, v205
	global_store_short v66, v205, s[10:11] offset:2112
	s_waitcnt vmcnt(33)
	v_lshlrev_b32_e32 v208, 16, v208
	v_lshlrev_b32_e32 v209, 16, v209
	v_lshlrev_b32_e32 v210, 16, v210
	v_fmac_f32_e32 v209, v68, v208
	v_add_f32_e32 v208, v209, v210
	v_mul_f32_e32 v209, 0x3d372713, v208
	v_mul_f32_e32 v209, v208, v209
	v_fma_f32 v209, v208, v209, v208
	v_mul_f32_e32 v209, 0xbfcc422a, v209
	v_mul_f32_e32 v209, 0x3fb8aa3b, v209
	v_exp_f32_e32 v209, v209
	v_mul_f32_e32 v51, 0xbfb8aa3b, v51
	v_exp_f32_e32 v51, v51
	v_add_f32_e32 v209, 1.0, v209
	v_add_f32_e32 v51, 1.0, v51
	v_rcp_f32_e32 v209, v209
	v_rcp_f32_e32 v51, v51
	v_mul_f32_e32 v208, v208, v209
	v_mul_f32_e32 v208, v51, v208
	v_cvt_pk_bf16_f32 v208, v208, v208
	global_store_short v66, v208, s[10:11] offset:3072
	s_waitcnt vmcnt(31)
	v_lshlrev_b32_e32 v211, 16, v211
	v_lshlrev_b32_e32 v212, 16, v212
	v_lshlrev_b32_e32 v213, 16, v213
	v_fmac_f32_e32 v212, v69, v211
	v_add_f32_e32 v211, v212, v213
	v_mul_f32_e32 v212, 0x3d372713, v211
	v_mul_f32_e32 v212, v211, v212
	v_fma_f32 v212, v211, v212, v211
	v_mul_f32_e32 v212, 0xbfcc422a, v212
	v_mul_f32_e32 v212, 0x3fb8aa3b, v212
	v_exp_f32_e32 v212, v212
	v_mul_f32_e32 v35, 0xbfb8aa3b, v35
	v_exp_f32_e32 v35, v35
	v_add_f32_e32 v212, 1.0, v212
	v_add_f32_e32 v35, 1.0, v35
	v_rcp_f32_e32 v212, v212
	v_rcp_f32_e32 v35, v35
	v_mul_f32_e32 v211, v211, v212
	v_mul_f32_e32 v211, v35, v211
	v_cvt_pk_bf16_f32 v211, v211, v211
	global_store_short v66, v211, s[10:11] offset:3136
	v_add_u32_e32 v66, 0x4000, v65
	global_load_ushort v190, v66, s[0:1]
	global_load_ushort v191, v66, s[4:5]
	global_load_ushort v192, v66, s[6:7]
	global_load_ushort v193, v66, s[0:1] offset:64
	global_load_ushort v194, v66, s[4:5] offset:64
	global_load_ushort v195, v66, s[6:7] offset:64
	global_load_ushort v196, v66, s[0:1] offset:1024
	global_load_ushort v197, v66, s[4:5] offset:1024
	global_load_ushort v198, v66, s[6:7] offset:1024
	global_load_ushort v199, v66, s[0:1] offset:1088
	global_load_ushort v200, v66, s[4:5] offset:1088
	global_load_ushort v201, v66, s[6:7] offset:1088
	global_load_ushort v202, v66, s[0:1] offset:2048
	global_load_ushort v203, v66, s[4:5] offset:2048
	global_load_ushort v204, v66, s[6:7] offset:2048
	global_load_ushort v205, v66, s[0:1] offset:2112
	global_load_ushort v206, v66, s[4:5] offset:2112
	global_load_ushort v207, v66, s[6:7] offset:2112
	global_load_ushort v208, v66, s[0:1] offset:3072
	global_load_ushort v209, v66, s[4:5] offset:3072
	global_load_ushort v210, v66, s[6:7] offset:3072
	global_load_ushort v211, v66, s[0:1] offset:3136
	global_load_ushort v212, v66, s[4:5] offset:3136
	global_load_ushort v213, v66, s[6:7] offset:3136
	s_waitcnt vmcnt(53)
	v_lshlrev_b32_e32 v214, 16, v214
	v_lshlrev_b32_e32 v215, 16, v215
	v_lshlrev_b32_e32 v216, 16, v216
	v_fmac_f32_e32 v215, v68, v214
	v_add_f32_e32 v214, v215, v216
	v_mul_f32_e32 v215, 0x3d372713, v214
	v_mul_f32_e32 v215, v214, v215
	v_fma_f32 v215, v214, v215, v214
	v_mul_f32_e32 v215, 0xbfcc422a, v215
	v_mul_f32_e32 v215, 0x3fb8aa3b, v215
	v_exp_f32_e32 v215, v215
	v_mul_f32_e32 v52, 0xbfb8aa3b, v52
	v_exp_f32_e32 v52, v52
	v_add_f32_e32 v215, 1.0, v215
	v_add_f32_e32 v52, 1.0, v52
	v_rcp_f32_e32 v215, v215
	v_rcp_f32_e32 v52, v52
	v_mul_f32_e32 v214, v214, v215
	v_mul_f32_e32 v214, v52, v214
	v_cvt_pk_bf16_f32 v214, v214, v214
	global_store_short v67, v214, s[10:11]
	s_waitcnt vmcnt(51)
	v_lshlrev_b32_e32 v217, 16, v217
	v_lshlrev_b32_e32 v218, 16, v218
	v_lshlrev_b32_e32 v219, 16, v219
	v_fmac_f32_e32 v218, v69, v217
	v_add_f32_e32 v217, v218, v219
	v_mul_f32_e32 v218, 0x3d372713, v217
	v_mul_f32_e32 v218, v217, v218
	v_fma_f32 v218, v217, v218, v217
	v_mul_f32_e32 v218, 0xbfcc422a, v218
	v_mul_f32_e32 v218, 0x3fb8aa3b, v218
	v_exp_f32_e32 v218, v218
	v_mul_f32_e32 v36, 0xbfb8aa3b, v36
	v_exp_f32_e32 v36, v36
	v_add_f32_e32 v218, 1.0, v218
	v_add_f32_e32 v36, 1.0, v36
	v_rcp_f32_e32 v218, v218
	v_rcp_f32_e32 v36, v36
	v_mul_f32_e32 v217, v217, v218
	v_mul_f32_e32 v217, v36, v217
	v_cvt_pk_bf16_f32 v217, v217, v217
	global_store_short v67, v217, s[10:11] offset:64
	s_waitcnt vmcnt(49)
	v_lshlrev_b32_e32 v220, 16, v220
	v_lshlrev_b32_e32 v221, 16, v221
	v_lshlrev_b32_e32 v222, 16, v222
	v_fmac_f32_e32 v221, v68, v220
	v_add_f32_e32 v220, v221, v222
	v_mul_f32_e32 v221, 0x3d372713, v220
	v_mul_f32_e32 v221, v220, v221
	v_fma_f32 v221, v220, v221, v220
	v_mul_f32_e32 v221, 0xbfcc422a, v221
	v_mul_f32_e32 v221, 0x3fb8aa3b, v221
	v_exp_f32_e32 v221, v221
	v_mul_f32_e32 v53, 0xbfb8aa3b, v53
	v_exp_f32_e32 v53, v53
	v_add_f32_e32 v221, 1.0, v221
	v_add_f32_e32 v53, 1.0, v53
	v_rcp_f32_e32 v221, v221
	v_rcp_f32_e32 v53, v53
	v_mul_f32_e32 v220, v220, v221
	v_mul_f32_e32 v220, v53, v220
	v_cvt_pk_bf16_f32 v220, v220, v220
	global_store_short v67, v220, s[10:11] offset:1024
	s_waitcnt vmcnt(47)
	v_lshlrev_b32_e32 v223, 16, v223
	v_lshlrev_b32_e32 v224, 16, v224
	v_lshlrev_b32_e32 v225, 16, v225
	v_fmac_f32_e32 v224, v69, v223
	v_add_f32_e32 v223, v224, v225
	v_mul_f32_e32 v224, 0x3d372713, v223
	v_mul_f32_e32 v224, v223, v224
	v_fma_f32 v224, v223, v224, v223
	v_mul_f32_e32 v224, 0xbfcc422a, v224
	v_mul_f32_e32 v224, 0x3fb8aa3b, v224
	v_exp_f32_e32 v224, v224
	v_mul_f32_e32 v37, 0xbfb8aa3b, v37
	v_exp_f32_e32 v37, v37
	v_add_f32_e32 v224, 1.0, v224
	v_add_f32_e32 v37, 1.0, v37
	v_rcp_f32_e32 v224, v224
	v_rcp_f32_e32 v37, v37
	v_mul_f32_e32 v223, v223, v224
	v_mul_f32_e32 v223, v37, v223
	v_cvt_pk_bf16_f32 v223, v223, v223
	global_store_short v67, v223, s[10:11] offset:1088
	s_waitcnt vmcnt(45)
	v_lshlrev_b32_e32 v226, 16, v226
	v_lshlrev_b32_e32 v227, 16, v227
	v_lshlrev_b32_e32 v228, 16, v228
	v_fmac_f32_e32 v227, v68, v226
	v_add_f32_e32 v226, v227, v228
	v_mul_f32_e32 v227, 0x3d372713, v226
	v_mul_f32_e32 v227, v226, v227
	v_fma_f32 v227, v226, v227, v226
	v_mul_f32_e32 v227, 0xbfcc422a, v227
	v_mul_f32_e32 v227, 0x3fb8aa3b, v227
	v_exp_f32_e32 v227, v227
	v_mul_f32_e32 v54, 0xbfb8aa3b, v54
	v_exp_f32_e32 v54, v54
	v_add_f32_e32 v227, 1.0, v227
	v_add_f32_e32 v54, 1.0, v54
	v_rcp_f32_e32 v227, v227
	v_rcp_f32_e32 v54, v54
	v_mul_f32_e32 v226, v226, v227
	v_mul_f32_e32 v226, v54, v226
	v_cvt_pk_bf16_f32 v226, v226, v226
	global_store_short v67, v226, s[10:11] offset:2048
	s_waitcnt vmcnt(43)
	v_lshlrev_b32_e32 v229, 16, v229
	v_lshlrev_b32_e32 v230, 16, v230
	v_lshlrev_b32_e32 v231, 16, v231
	v_fmac_f32_e32 v230, v69, v229
	v_add_f32_e32 v229, v230, v231
	v_mul_f32_e32 v230, 0x3d372713, v229
	v_mul_f32_e32 v230, v229, v230
	v_fma_f32 v230, v229, v230, v229
	v_mul_f32_e32 v230, 0xbfcc422a, v230
	v_mul_f32_e32 v230, 0x3fb8aa3b, v230
	v_exp_f32_e32 v230, v230
	v_mul_f32_e32 v38, 0xbfb8aa3b, v38
	v_exp_f32_e32 v38, v38
	v_add_f32_e32 v230, 1.0, v230
	v_add_f32_e32 v38, 1.0, v38
	v_rcp_f32_e32 v230, v230
	v_rcp_f32_e32 v38, v38
	v_mul_f32_e32 v229, v229, v230
	v_mul_f32_e32 v229, v38, v229
	v_cvt_pk_bf16_f32 v229, v229, v229
	global_store_short v67, v229, s[10:11] offset:2112
	s_waitcnt vmcnt(41)
	v_lshlrev_b32_e32 v232, 16, v232
	v_lshlrev_b32_e32 v233, 16, v233
	v_lshlrev_b32_e32 v70, 16, v70
	v_fmac_f32_e32 v233, v68, v232
	v_add_f32_e32 v232, v233, v70
	v_mul_f32_e32 v233, 0x3d372713, v232
	v_mul_f32_e32 v233, v232, v233
	v_fma_f32 v233, v232, v233, v232
	v_mul_f32_e32 v233, 0xbfcc422a, v233
	v_mul_f32_e32 v233, 0x3fb8aa3b, v233
	v_exp_f32_e32 v233, v233
	v_mul_f32_e32 v55, 0xbfb8aa3b, v55
	v_exp_f32_e32 v55, v55
	v_add_f32_e32 v233, 1.0, v233
	v_add_f32_e32 v55, 1.0, v55
	v_rcp_f32_e32 v233, v233
	v_rcp_f32_e32 v55, v55
	v_mul_f32_e32 v232, v232, v233
	v_mul_f32_e32 v232, v55, v232
	v_cvt_pk_bf16_f32 v232, v232, v232
	global_store_short v67, v232, s[10:11] offset:3072
	s_waitcnt vmcnt(39)
	v_lshlrev_b32_e32 v71, 16, v71
	v_lshlrev_b32_e32 v72, 16, v72
	v_lshlrev_b32_e32 v73, 16, v73
	v_fmac_f32_e32 v72, v69, v71
	v_add_f32_e32 v71, v72, v73
	v_mul_f32_e32 v72, 0x3d372713, v71
	v_mul_f32_e32 v72, v71, v72
	v_fma_f32 v72, v71, v72, v71
	v_mul_f32_e32 v72, 0xbfcc422a, v72
	v_mul_f32_e32 v72, 0x3fb8aa3b, v72
	v_exp_f32_e32 v72, v72
	v_mul_f32_e32 v39, 0xbfb8aa3b, v39
	v_exp_f32_e32 v39, v39
	v_add_f32_e32 v72, 1.0, v72
	v_add_f32_e32 v39, 1.0, v39
	v_rcp_f32_e32 v72, v72
	v_rcp_f32_e32 v39, v39
	v_mul_f32_e32 v71, v71, v72
	v_mul_f32_e32 v71, v39, v71
	v_cvt_pk_bf16_f32 v71, v71, v71
	global_store_short v67, v71, s[10:11] offset:3136
	v_add_u32_e32 v67, 0x6000, v65
	global_load_ushort v214, v67, s[0:1]
	global_load_ushort v215, v67, s[4:5]
	global_load_ushort v216, v67, s[6:7]
	global_load_ushort v217, v67, s[0:1] offset:64
	global_load_ushort v218, v67, s[4:5] offset:64
	global_load_ushort v219, v67, s[6:7] offset:64
	global_load_ushort v220, v67, s[0:1] offset:1024
	global_load_ushort v221, v67, s[4:5] offset:1024
	global_load_ushort v222, v67, s[6:7] offset:1024
	global_load_ushort v223, v67, s[0:1] offset:1088
	global_load_ushort v224, v67, s[4:5] offset:1088
	global_load_ushort v225, v67, s[6:7] offset:1088
	global_load_ushort v226, v67, s[0:1] offset:2048
	global_load_ushort v227, v67, s[4:5] offset:2048
	global_load_ushort v228, v67, s[6:7] offset:2048
	global_load_ushort v229, v67, s[0:1] offset:2112
	global_load_ushort v230, v67, s[4:5] offset:2112
	global_load_ushort v231, v67, s[6:7] offset:2112
	global_load_ushort v232, v67, s[0:1] offset:3072
	global_load_ushort v233, v67, s[4:5] offset:3072
	global_load_ushort v70, v67, s[6:7] offset:3072
	global_load_ushort v71, v67, s[0:1] offset:3136
	global_load_ushort v72, v67, s[4:5] offset:3136
	global_load_ushort v73, v67, s[6:7] offset:3136
	s_waitcnt vmcnt(53)
	v_lshlrev_b32_e32 v190, 16, v190
	v_lshlrev_b32_e32 v191, 16, v191
	v_lshlrev_b32_e32 v192, 16, v192
	v_fmac_f32_e32 v191, v68, v190
	v_add_f32_e32 v190, v191, v192
	v_mul_f32_e32 v191, 0x3d372713, v190
	v_mul_f32_e32 v191, v190, v191
	v_fma_f32 v191, v190, v191, v190
	v_mul_f32_e32 v191, 0xbfcc422a, v191
	v_mul_f32_e32 v191, 0x3fb8aa3b, v191
	v_exp_f32_e32 v191, v191
	v_mul_f32_e32 v56, 0xbfb8aa3b, v56
	v_exp_f32_e32 v56, v56
	v_add_f32_e32 v191, 1.0, v191
	v_add_f32_e32 v56, 1.0, v56
	v_rcp_f32_e32 v191, v191
	v_rcp_f32_e32 v56, v56
	v_mul_f32_e32 v190, v190, v191
	v_mul_f32_e32 v190, v56, v190
	v_cvt_pk_bf16_f32 v190, v190, v190
	global_store_short v66, v190, s[10:11]
	s_waitcnt vmcnt(51)
	v_lshlrev_b32_e32 v193, 16, v193
	v_lshlrev_b32_e32 v194, 16, v194
	v_lshlrev_b32_e32 v195, 16, v195
	v_fmac_f32_e32 v194, v69, v193
	v_add_f32_e32 v193, v194, v195
	v_mul_f32_e32 v194, 0x3d372713, v193
	v_mul_f32_e32 v194, v193, v194
	v_fma_f32 v194, v193, v194, v193
	v_mul_f32_e32 v194, 0xbfcc422a, v194
	v_mul_f32_e32 v194, 0x3fb8aa3b, v194
	v_exp_f32_e32 v194, v194
	v_mul_f32_e32 v40, 0xbfb8aa3b, v40
	v_exp_f32_e32 v40, v40
	v_add_f32_e32 v194, 1.0, v194
	v_add_f32_e32 v40, 1.0, v40
	v_rcp_f32_e32 v194, v194
	v_rcp_f32_e32 v40, v40
	v_mul_f32_e32 v193, v193, v194
	v_mul_f32_e32 v193, v40, v193
	v_cvt_pk_bf16_f32 v193, v193, v193
	global_store_short v66, v193, s[10:11] offset:64
	s_waitcnt vmcnt(49)
	v_lshlrev_b32_e32 v196, 16, v196
	v_lshlrev_b32_e32 v197, 16, v197
	v_lshlrev_b32_e32 v198, 16, v198
	v_fmac_f32_e32 v197, v68, v196
	v_add_f32_e32 v196, v197, v198
	v_mul_f32_e32 v197, 0x3d372713, v196
	v_mul_f32_e32 v197, v196, v197
	v_fma_f32 v197, v196, v197, v196
	v_mul_f32_e32 v197, 0xbfcc422a, v197
	v_mul_f32_e32 v197, 0x3fb8aa3b, v197
	v_exp_f32_e32 v197, v197
	v_mul_f32_e32 v57, 0xbfb8aa3b, v57
	v_exp_f32_e32 v57, v57
	v_add_f32_e32 v197, 1.0, v197
	v_add_f32_e32 v57, 1.0, v57
	v_rcp_f32_e32 v197, v197
	v_rcp_f32_e32 v57, v57
	v_mul_f32_e32 v196, v196, v197
	v_mul_f32_e32 v196, v57, v196
	v_cvt_pk_bf16_f32 v196, v196, v196
	global_store_short v66, v196, s[10:11] offset:1024
	s_waitcnt vmcnt(47)
	v_lshlrev_b32_e32 v199, 16, v199
	v_lshlrev_b32_e32 v200, 16, v200
	v_lshlrev_b32_e32 v201, 16, v201
	v_fmac_f32_e32 v200, v69, v199
	v_add_f32_e32 v199, v200, v201
	v_mul_f32_e32 v200, 0x3d372713, v199
	v_mul_f32_e32 v200, v199, v200
	v_fma_f32 v200, v199, v200, v199
	v_mul_f32_e32 v200, 0xbfcc422a, v200
	v_mul_f32_e32 v200, 0x3fb8aa3b, v200
	v_exp_f32_e32 v200, v200
	v_mul_f32_e32 v41, 0xbfb8aa3b, v41
	v_exp_f32_e32 v41, v41
	v_add_f32_e32 v200, 1.0, v200
	v_add_f32_e32 v41, 1.0, v41
	v_rcp_f32_e32 v200, v200
	v_rcp_f32_e32 v41, v41
	v_mul_f32_e32 v199, v199, v200
	v_mul_f32_e32 v199, v41, v199
	v_cvt_pk_bf16_f32 v199, v199, v199
	global_store_short v66, v199, s[10:11] offset:1088
	s_waitcnt vmcnt(45)
	v_lshlrev_b32_e32 v202, 16, v202
	v_lshlrev_b32_e32 v203, 16, v203
	v_lshlrev_b32_e32 v204, 16, v204
	v_fmac_f32_e32 v203, v68, v202
	v_add_f32_e32 v202, v203, v204
	v_mul_f32_e32 v203, 0x3d372713, v202
	v_mul_f32_e32 v203, v202, v203
	v_fma_f32 v203, v202, v203, v202
	v_mul_f32_e32 v203, 0xbfcc422a, v203
	v_mul_f32_e32 v203, 0x3fb8aa3b, v203
	v_exp_f32_e32 v203, v203
	v_mul_f32_e32 v58, 0xbfb8aa3b, v58
	v_exp_f32_e32 v58, v58
	v_add_f32_e32 v203, 1.0, v203
	v_add_f32_e32 v58, 1.0, v58
	v_rcp_f32_e32 v203, v203
	v_rcp_f32_e32 v58, v58
	v_mul_f32_e32 v202, v202, v203
	v_mul_f32_e32 v202, v58, v202
	v_cvt_pk_bf16_f32 v202, v202, v202
	global_store_short v66, v202, s[10:11] offset:2048
	s_waitcnt vmcnt(43)
	v_lshlrev_b32_e32 v205, 16, v205
	v_lshlrev_b32_e32 v206, 16, v206
	v_lshlrev_b32_e32 v207, 16, v207
	v_fmac_f32_e32 v206, v69, v205
	v_add_f32_e32 v205, v206, v207
	v_mul_f32_e32 v206, 0x3d372713, v205
	v_mul_f32_e32 v206, v205, v206
	v_fma_f32 v206, v205, v206, v205
	v_mul_f32_e32 v206, 0xbfcc422a, v206
	v_mul_f32_e32 v206, 0x3fb8aa3b, v206
	v_exp_f32_e32 v206, v206
	v_mul_f32_e32 v42, 0xbfb8aa3b, v42
	v_exp_f32_e32 v42, v42
	v_add_f32_e32 v206, 1.0, v206
	v_add_f32_e32 v42, 1.0, v42
	v_rcp_f32_e32 v206, v206
	v_rcp_f32_e32 v42, v42
	v_mul_f32_e32 v205, v205, v206
	v_mul_f32_e32 v205, v42, v205
	v_cvt_pk_bf16_f32 v205, v205, v205
	global_store_short v66, v205, s[10:11] offset:2112
	s_waitcnt vmcnt(41)
	v_lshlrev_b32_e32 v208, 16, v208
	v_lshlrev_b32_e32 v209, 16, v209
	v_lshlrev_b32_e32 v210, 16, v210
	v_fmac_f32_e32 v209, v68, v208
	v_add_f32_e32 v208, v209, v210
	v_mul_f32_e32 v209, 0x3d372713, v208
	v_mul_f32_e32 v209, v208, v209
	v_fma_f32 v209, v208, v209, v208
	v_mul_f32_e32 v209, 0xbfcc422a, v209
	v_mul_f32_e32 v209, 0x3fb8aa3b, v209
	v_exp_f32_e32 v209, v209
	v_mul_f32_e32 v59, 0xbfb8aa3b, v59
	v_exp_f32_e32 v59, v59
	v_add_f32_e32 v209, 1.0, v209
	v_add_f32_e32 v59, 1.0, v59
	v_rcp_f32_e32 v209, v209
	v_rcp_f32_e32 v59, v59
	v_mul_f32_e32 v208, v208, v209
	v_mul_f32_e32 v208, v59, v208
	v_cvt_pk_bf16_f32 v208, v208, v208
	global_store_short v66, v208, s[10:11] offset:3072
	s_waitcnt vmcnt(39)
	v_lshlrev_b32_e32 v211, 16, v211
	v_lshlrev_b32_e32 v212, 16, v212
	v_lshlrev_b32_e32 v213, 16, v213
	v_fmac_f32_e32 v212, v69, v211
	v_add_f32_e32 v211, v212, v213
	v_mul_f32_e32 v212, 0x3d372713, v211
	v_mul_f32_e32 v212, v211, v212
	v_fma_f32 v212, v211, v212, v211
	v_mul_f32_e32 v212, 0xbfcc422a, v212
	v_mul_f32_e32 v212, 0x3fb8aa3b, v212
	v_exp_f32_e32 v212, v212
	v_mul_f32_e32 v43, 0xbfb8aa3b, v43
	v_exp_f32_e32 v43, v43
	v_add_f32_e32 v212, 1.0, v212
	v_add_f32_e32 v43, 1.0, v43
	v_rcp_f32_e32 v212, v212
	v_rcp_f32_e32 v43, v43
	v_mul_f32_e32 v211, v211, v212
	v_mul_f32_e32 v211, v43, v211
	v_cvt_pk_bf16_f32 v211, v211, v211
	global_store_short v66, v211, s[10:11] offset:3136
	v_add_u32_e32 v66, 0x8000, v65
	global_load_ushort v190, v66, s[0:1]
	global_load_ushort v191, v66, s[4:5]
	global_load_ushort v192, v66, s[6:7]
	global_load_ushort v193, v66, s[0:1] offset:64
	global_load_ushort v194, v66, s[4:5] offset:64
	global_load_ushort v195, v66, s[6:7] offset:64
	global_load_ushort v196, v66, s[0:1] offset:1024
	global_load_ushort v197, v66, s[4:5] offset:1024
	global_load_ushort v198, v66, s[6:7] offset:1024
	global_load_ushort v199, v66, s[0:1] offset:1088
	global_load_ushort v200, v66, s[4:5] offset:1088
	global_load_ushort v201, v66, s[6:7] offset:1088
	global_load_ushort v202, v66, s[0:1] offset:2048
	global_load_ushort v203, v66, s[4:5] offset:2048
	global_load_ushort v204, v66, s[6:7] offset:2048
	global_load_ushort v205, v66, s[0:1] offset:2112
	global_load_ushort v206, v66, s[4:5] offset:2112
	global_load_ushort v207, v66, s[6:7] offset:2112
	global_load_ushort v208, v66, s[0:1] offset:3072
	global_load_ushort v209, v66, s[4:5] offset:3072
	global_load_ushort v210, v66, s[6:7] offset:3072
	global_load_ushort v211, v66, s[0:1] offset:3136
	global_load_ushort v212, v66, s[4:5] offset:3136
	global_load_ushort v213, v66, s[6:7] offset:3136
	s_waitcnt vmcnt(53)
	v_lshlrev_b32_e32 v214, 16, v214
	v_lshlrev_b32_e32 v215, 16, v215
	v_lshlrev_b32_e32 v216, 16, v216
	v_fmac_f32_e32 v215, v68, v214
	v_add_f32_e32 v214, v215, v216
	v_mul_f32_e32 v215, 0x3d372713, v214
	v_mul_f32_e32 v215, v214, v215
	v_fma_f32 v215, v214, v215, v214
	v_mul_f32_e32 v215, 0xbfcc422a, v215
	v_mul_f32_e32 v215, 0x3fb8aa3b, v215
	v_exp_f32_e32 v215, v215
	v_mul_f32_e32 v60, 0xbfb8aa3b, v60
	v_exp_f32_e32 v60, v60
	v_add_f32_e32 v215, 1.0, v215
	v_add_f32_e32 v60, 1.0, v60
	v_rcp_f32_e32 v215, v215
	v_rcp_f32_e32 v60, v60
	v_mul_f32_e32 v214, v214, v215
	v_mul_f32_e32 v214, v60, v214
	v_cvt_pk_bf16_f32 v214, v214, v214
	global_store_short v67, v214, s[10:11]
	s_waitcnt vmcnt(51)
	v_lshlrev_b32_e32 v217, 16, v217
	v_lshlrev_b32_e32 v218, 16, v218
	v_lshlrev_b32_e32 v219, 16, v219
	v_fmac_f32_e32 v218, v69, v217
	v_add_f32_e32 v217, v218, v219
	v_mul_f32_e32 v218, 0x3d372713, v217
	v_mul_f32_e32 v218, v217, v218
	v_fma_f32 v218, v217, v218, v217
	v_mul_f32_e32 v218, 0xbfcc422a, v218
	v_mul_f32_e32 v218, 0x3fb8aa3b, v218
	v_exp_f32_e32 v218, v218
	v_mul_f32_e32 v44, 0xbfb8aa3b, v44
	v_exp_f32_e32 v44, v44
	v_add_f32_e32 v218, 1.0, v218
	v_add_f32_e32 v44, 1.0, v44
	v_rcp_f32_e32 v218, v218
	v_rcp_f32_e32 v44, v44
	v_mul_f32_e32 v217, v217, v218
	v_mul_f32_e32 v217, v44, v217
	v_cvt_pk_bf16_f32 v217, v217, v217
	global_store_short v67, v217, s[10:11] offset:64
	s_waitcnt vmcnt(49)
	v_lshlrev_b32_e32 v220, 16, v220
	v_lshlrev_b32_e32 v221, 16, v221
	v_lshlrev_b32_e32 v222, 16, v222
	v_fmac_f32_e32 v221, v68, v220
	v_add_f32_e32 v220, v221, v222
	v_mul_f32_e32 v221, 0x3d372713, v220
	v_mul_f32_e32 v221, v220, v221
	v_fma_f32 v221, v220, v221, v220
	v_mul_f32_e32 v221, 0xbfcc422a, v221
	v_mul_f32_e32 v221, 0x3fb8aa3b, v221
	v_exp_f32_e32 v221, v221
	v_mul_f32_e32 v61, 0xbfb8aa3b, v61
	v_exp_f32_e32 v61, v61
	v_add_f32_e32 v221, 1.0, v221
	v_add_f32_e32 v61, 1.0, v61
	v_rcp_f32_e32 v221, v221
	v_rcp_f32_e32 v61, v61
	v_mul_f32_e32 v220, v220, v221
	v_mul_f32_e32 v220, v61, v220
	v_cvt_pk_bf16_f32 v220, v220, v220
	global_store_short v67, v220, s[10:11] offset:1024
	s_waitcnt vmcnt(47)
	v_lshlrev_b32_e32 v223, 16, v223
	v_lshlrev_b32_e32 v224, 16, v224
	v_lshlrev_b32_e32 v225, 16, v225
	v_fmac_f32_e32 v224, v69, v223
	v_add_f32_e32 v223, v224, v225
	v_mul_f32_e32 v224, 0x3d372713, v223
	v_mul_f32_e32 v224, v223, v224
	v_fma_f32 v224, v223, v224, v223
	v_mul_f32_e32 v224, 0xbfcc422a, v224
	v_mul_f32_e32 v224, 0x3fb8aa3b, v224
	v_exp_f32_e32 v224, v224
	v_mul_f32_e32 v45, 0xbfb8aa3b, v45
	v_exp_f32_e32 v45, v45
	v_add_f32_e32 v224, 1.0, v224
	v_add_f32_e32 v45, 1.0, v45
	v_rcp_f32_e32 v224, v224
	v_rcp_f32_e32 v45, v45
	v_mul_f32_e32 v223, v223, v224
	v_mul_f32_e32 v223, v45, v223
	v_cvt_pk_bf16_f32 v223, v223, v223
	global_store_short v67, v223, s[10:11] offset:1088
	s_waitcnt vmcnt(45)
	v_lshlrev_b32_e32 v226, 16, v226
	v_lshlrev_b32_e32 v227, 16, v227
	v_lshlrev_b32_e32 v228, 16, v228
	v_fmac_f32_e32 v227, v68, v226
	v_add_f32_e32 v226, v227, v228
	v_mul_f32_e32 v227, 0x3d372713, v226
	v_mul_f32_e32 v227, v226, v227
	v_fma_f32 v227, v226, v227, v226
	v_mul_f32_e32 v227, 0xbfcc422a, v227
	v_mul_f32_e32 v227, 0x3fb8aa3b, v227
	v_exp_f32_e32 v227, v227
	v_mul_f32_e32 v62, 0xbfb8aa3b, v62
	v_exp_f32_e32 v62, v62
	v_add_f32_e32 v227, 1.0, v227
	v_add_f32_e32 v62, 1.0, v62
	v_rcp_f32_e32 v227, v227
	v_rcp_f32_e32 v62, v62
	v_mul_f32_e32 v226, v226, v227
	v_mul_f32_e32 v226, v62, v226
	v_cvt_pk_bf16_f32 v226, v226, v226
	global_store_short v67, v226, s[10:11] offset:2048
	s_waitcnt vmcnt(43)
	v_lshlrev_b32_e32 v229, 16, v229
	v_lshlrev_b32_e32 v230, 16, v230
	v_lshlrev_b32_e32 v231, 16, v231
	v_fmac_f32_e32 v230, v69, v229
	v_add_f32_e32 v229, v230, v231
	v_mul_f32_e32 v230, 0x3d372713, v229
	v_mul_f32_e32 v230, v229, v230
	v_fma_f32 v230, v229, v230, v229
	v_mul_f32_e32 v230, 0xbfcc422a, v230
	v_mul_f32_e32 v230, 0x3fb8aa3b, v230
	v_exp_f32_e32 v230, v230
	v_mul_f32_e32 v46, 0xbfb8aa3b, v46
	v_exp_f32_e32 v46, v46
	v_add_f32_e32 v230, 1.0, v230
	v_add_f32_e32 v46, 1.0, v46
	v_rcp_f32_e32 v230, v230
	v_rcp_f32_e32 v46, v46
	v_mul_f32_e32 v229, v229, v230
	v_mul_f32_e32 v229, v46, v229
	v_cvt_pk_bf16_f32 v229, v229, v229
	global_store_short v67, v229, s[10:11] offset:2112
	s_waitcnt vmcnt(41)
	v_lshlrev_b32_e32 v232, 16, v232
	v_lshlrev_b32_e32 v233, 16, v233
	v_lshlrev_b32_e32 v70, 16, v70
	v_fmac_f32_e32 v233, v68, v232
	v_add_f32_e32 v232, v233, v70
	v_mul_f32_e32 v233, 0x3d372713, v232
	v_mul_f32_e32 v233, v232, v233
	v_fma_f32 v233, v232, v233, v232
	v_mul_f32_e32 v233, 0xbfcc422a, v233
	v_mul_f32_e32 v233, 0x3fb8aa3b, v233
	v_exp_f32_e32 v233, v233
	v_mul_f32_e32 v63, 0xbfb8aa3b, v63
	v_exp_f32_e32 v63, v63
	v_add_f32_e32 v233, 1.0, v233
	v_add_f32_e32 v63, 1.0, v63
	v_rcp_f32_e32 v233, v233
	v_rcp_f32_e32 v63, v63
	v_mul_f32_e32 v232, v232, v233
	v_mul_f32_e32 v232, v63, v232
	v_cvt_pk_bf16_f32 v232, v232, v232
	global_store_short v67, v232, s[10:11] offset:3072
	s_waitcnt vmcnt(39)
	v_lshlrev_b32_e32 v71, 16, v71
	v_lshlrev_b32_e32 v72, 16, v72
	v_lshlrev_b32_e32 v73, 16, v73
	v_fmac_f32_e32 v72, v69, v71
	v_add_f32_e32 v71, v72, v73
	v_mul_f32_e32 v72, 0x3d372713, v71
	v_mul_f32_e32 v72, v71, v72
	v_fma_f32 v72, v71, v72, v71
	v_mul_f32_e32 v72, 0xbfcc422a, v72
	v_mul_f32_e32 v72, 0x3fb8aa3b, v72
	v_exp_f32_e32 v72, v72
	v_mul_f32_e32 v47, 0xbfb8aa3b, v47
	v_exp_f32_e32 v47, v47
	v_add_f32_e32 v72, 1.0, v72
	v_add_f32_e32 v47, 1.0, v47
	v_rcp_f32_e32 v72, v72
	v_rcp_f32_e32 v47, v47
	v_mul_f32_e32 v71, v71, v72
	v_mul_f32_e32 v71, v47, v71
	v_cvt_pk_bf16_f32 v71, v71, v71
	global_store_short v67, v71, s[10:11] offset:3136
	v_add_u32_e32 v67, 0xa000, v65
	global_load_ushort v214, v67, s[0:1]
	global_load_ushort v215, v67, s[4:5]
	global_load_ushort v216, v67, s[6:7]
	global_load_ushort v217, v67, s[0:1] offset:64
	global_load_ushort v218, v67, s[4:5] offset:64
	global_load_ushort v219, v67, s[6:7] offset:64
	global_load_ushort v220, v67, s[0:1] offset:1024
	global_load_ushort v221, v67, s[4:5] offset:1024
	global_load_ushort v222, v67, s[6:7] offset:1024
	global_load_ushort v223, v67, s[0:1] offset:1088
	global_load_ushort v224, v67, s[4:5] offset:1088
	global_load_ushort v225, v67, s[6:7] offset:1088
	global_load_ushort v226, v67, s[0:1] offset:2048
	global_load_ushort v227, v67, s[4:5] offset:2048
	global_load_ushort v228, v67, s[6:7] offset:2048
	global_load_ushort v229, v67, s[0:1] offset:2112
	global_load_ushort v230, v67, s[4:5] offset:2112
	global_load_ushort v231, v67, s[6:7] offset:2112
	global_load_ushort v232, v67, s[0:1] offset:3072
	global_load_ushort v233, v67, s[4:5] offset:3072
	global_load_ushort v70, v67, s[6:7] offset:3072
	global_load_ushort v71, v67, s[0:1] offset:3136
	global_load_ushort v72, v67, s[4:5] offset:3136
	global_load_ushort v73, v67, s[6:7] offset:3136
	s_waitcnt vmcnt(53)
	v_lshlrev_b32_e32 v190, 16, v190
	v_lshlrev_b32_e32 v191, 16, v191
	v_lshlrev_b32_e32 v192, 16, v192
	v_fmac_f32_e32 v191, v68, v190
	v_add_f32_e32 v190, v191, v192
	v_mul_f32_e32 v191, 0x3d372713, v190
	v_mul_f32_e32 v191, v190, v191
	v_fma_f32 v191, v190, v191, v190
	v_mul_f32_e32 v191, 0xbfcc422a, v191
	v_mul_f32_e32 v191, 0x3fb8aa3b, v191
	v_exp_f32_e32 v191, v191
	v_mul_f32_e32 v16, 0xbfb8aa3b, v16
	v_exp_f32_e32 v16, v16
	v_add_f32_e32 v191, 1.0, v191
	v_add_f32_e32 v16, 1.0, v16
	v_rcp_f32_e32 v191, v191
	v_rcp_f32_e32 v16, v16
	v_mul_f32_e32 v190, v190, v191
	v_mul_f32_e32 v190, v16, v190
	v_cvt_pk_bf16_f32 v190, v190, v190
	global_store_short v66, v190, s[10:11]
	s_waitcnt vmcnt(51)
	v_lshlrev_b32_e32 v193, 16, v193
	v_lshlrev_b32_e32 v194, 16, v194
	v_lshlrev_b32_e32 v195, 16, v195
	v_fmac_f32_e32 v194, v69, v193
	v_add_f32_e32 v193, v194, v195
	v_mul_f32_e32 v194, 0x3d372713, v193
	v_mul_f32_e32 v194, v193, v194
	v_fma_f32 v194, v193, v194, v193
	v_mul_f32_e32 v194, 0xbfcc422a, v194
	v_mul_f32_e32 v194, 0x3fb8aa3b, v194
	v_exp_f32_e32 v194, v194
	v_mul_f32_e32 v0, 0xbfb8aa3b, v0
	v_exp_f32_e32 v0, v0
	v_add_f32_e32 v194, 1.0, v194
	v_add_f32_e32 v0, 1.0, v0
	v_rcp_f32_e32 v194, v194
	v_rcp_f32_e32 v0, v0
	v_mul_f32_e32 v193, v193, v194
	v_mul_f32_e32 v193, v0, v193
	v_cvt_pk_bf16_f32 v193, v193, v193
	global_store_short v66, v193, s[10:11] offset:64
	s_waitcnt vmcnt(49)
	v_lshlrev_b32_e32 v196, 16, v196
	v_lshlrev_b32_e32 v197, 16, v197
	v_lshlrev_b32_e32 v198, 16, v198
	v_fmac_f32_e32 v197, v68, v196
	v_add_f32_e32 v196, v197, v198
	v_mul_f32_e32 v197, 0x3d372713, v196
	v_mul_f32_e32 v197, v196, v197
	v_fma_f32 v197, v196, v197, v196
	v_mul_f32_e32 v197, 0xbfcc422a, v197
	v_mul_f32_e32 v197, 0x3fb8aa3b, v197
	v_exp_f32_e32 v197, v197
	v_mul_f32_e32 v17, 0xbfb8aa3b, v17
	v_exp_f32_e32 v17, v17
	v_add_f32_e32 v197, 1.0, v197
	v_add_f32_e32 v17, 1.0, v17
	v_rcp_f32_e32 v197, v197
	v_rcp_f32_e32 v17, v17
	v_mul_f32_e32 v196, v196, v197
	v_mul_f32_e32 v196, v17, v196
	v_cvt_pk_bf16_f32 v196, v196, v196
	global_store_short v66, v196, s[10:11] offset:1024
	s_waitcnt vmcnt(47)
	v_lshlrev_b32_e32 v199, 16, v199
	v_lshlrev_b32_e32 v200, 16, v200
	v_lshlrev_b32_e32 v201, 16, v201
	v_fmac_f32_e32 v200, v69, v199
	v_add_f32_e32 v199, v200, v201
	v_mul_f32_e32 v200, 0x3d372713, v199
	v_mul_f32_e32 v200, v199, v200
	v_fma_f32 v200, v199, v200, v199
	v_mul_f32_e32 v200, 0xbfcc422a, v200
	v_mul_f32_e32 v200, 0x3fb8aa3b, v200
	v_exp_f32_e32 v200, v200
	v_mul_f32_e32 v1, 0xbfb8aa3b, v1
	v_exp_f32_e32 v1, v1
	v_add_f32_e32 v200, 1.0, v200
	v_add_f32_e32 v1, 1.0, v1
	v_rcp_f32_e32 v200, v200
	v_rcp_f32_e32 v1, v1
	v_mul_f32_e32 v199, v199, v200
	v_mul_f32_e32 v199, v1, v199
	v_cvt_pk_bf16_f32 v199, v199, v199
	global_store_short v66, v199, s[10:11] offset:1088
	s_waitcnt vmcnt(45)
	v_lshlrev_b32_e32 v202, 16, v202
	v_lshlrev_b32_e32 v203, 16, v203
	v_lshlrev_b32_e32 v204, 16, v204
	v_fmac_f32_e32 v203, v68, v202
	v_add_f32_e32 v202, v203, v204
	v_mul_f32_e32 v203, 0x3d372713, v202
	v_mul_f32_e32 v203, v202, v203
	v_fma_f32 v203, v202, v203, v202
	v_mul_f32_e32 v203, 0xbfcc422a, v203
	v_mul_f32_e32 v203, 0x3fb8aa3b, v203
	v_exp_f32_e32 v203, v203
	v_mul_f32_e32 v18, 0xbfb8aa3b, v18
	v_exp_f32_e32 v18, v18
	v_add_f32_e32 v203, 1.0, v203
	v_add_f32_e32 v18, 1.0, v18
	v_rcp_f32_e32 v203, v203
	v_rcp_f32_e32 v18, v18
	v_mul_f32_e32 v202, v202, v203
	v_mul_f32_e32 v202, v18, v202
	v_cvt_pk_bf16_f32 v202, v202, v202
	global_store_short v66, v202, s[10:11] offset:2048
	s_waitcnt vmcnt(43)
	v_lshlrev_b32_e32 v205, 16, v205
	v_lshlrev_b32_e32 v206, 16, v206
	v_lshlrev_b32_e32 v207, 16, v207
	v_fmac_f32_e32 v206, v69, v205
	v_add_f32_e32 v205, v206, v207
	v_mul_f32_e32 v206, 0x3d372713, v205
	v_mul_f32_e32 v206, v205, v206
	v_fma_f32 v206, v205, v206, v205
	v_mul_f32_e32 v206, 0xbfcc422a, v206
	v_mul_f32_e32 v206, 0x3fb8aa3b, v206
	v_exp_f32_e32 v206, v206
	v_mul_f32_e32 v2, 0xbfb8aa3b, v2
	v_exp_f32_e32 v2, v2
	v_add_f32_e32 v206, 1.0, v206
	v_add_f32_e32 v2, 1.0, v2
	v_rcp_f32_e32 v206, v206
	v_rcp_f32_e32 v2, v2
	v_mul_f32_e32 v205, v205, v206
	v_mul_f32_e32 v205, v2, v205
	v_cvt_pk_bf16_f32 v205, v205, v205
	global_store_short v66, v205, s[10:11] offset:2112
	s_waitcnt vmcnt(41)
	v_lshlrev_b32_e32 v208, 16, v208
	v_lshlrev_b32_e32 v209, 16, v209
	v_lshlrev_b32_e32 v210, 16, v210
	v_fmac_f32_e32 v209, v68, v208
	v_add_f32_e32 v208, v209, v210
	v_mul_f32_e32 v209, 0x3d372713, v208
	v_mul_f32_e32 v209, v208, v209
	v_fma_f32 v209, v208, v209, v208
	v_mul_f32_e32 v209, 0xbfcc422a, v209
	v_mul_f32_e32 v209, 0x3fb8aa3b, v209
	v_exp_f32_e32 v209, v209
	v_mul_f32_e32 v19, 0xbfb8aa3b, v19
	v_exp_f32_e32 v19, v19
	v_add_f32_e32 v209, 1.0, v209
	v_add_f32_e32 v19, 1.0, v19
	v_rcp_f32_e32 v209, v209
	v_rcp_f32_e32 v19, v19
	v_mul_f32_e32 v208, v208, v209
	v_mul_f32_e32 v208, v19, v208
	v_cvt_pk_bf16_f32 v208, v208, v208
	global_store_short v66, v208, s[10:11] offset:3072
	s_waitcnt vmcnt(39)
	v_lshlrev_b32_e32 v211, 16, v211
	v_lshlrev_b32_e32 v212, 16, v212
	v_lshlrev_b32_e32 v213, 16, v213
	v_fmac_f32_e32 v212, v69, v211
	v_add_f32_e32 v211, v212, v213
	v_mul_f32_e32 v212, 0x3d372713, v211
	v_mul_f32_e32 v212, v211, v212
	v_fma_f32 v212, v211, v212, v211
	v_mul_f32_e32 v212, 0xbfcc422a, v212
	v_mul_f32_e32 v212, 0x3fb8aa3b, v212
	v_exp_f32_e32 v212, v212
	v_mul_f32_e32 v3, 0xbfb8aa3b, v3
	v_exp_f32_e32 v3, v3
	v_add_f32_e32 v212, 1.0, v212
	v_add_f32_e32 v3, 1.0, v3
	v_rcp_f32_e32 v212, v212
	v_rcp_f32_e32 v3, v3
	v_mul_f32_e32 v211, v211, v212
	v_mul_f32_e32 v211, v3, v211
	v_cvt_pk_bf16_f32 v211, v211, v211
	global_store_short v66, v211, s[10:11] offset:3136
	v_add_u32_e32 v66, 0xc000, v65
	global_load_ushort v190, v66, s[0:1]
	global_load_ushort v191, v66, s[4:5]
	global_load_ushort v192, v66, s[6:7]
	global_load_ushort v193, v66, s[0:1] offset:64
	global_load_ushort v194, v66, s[4:5] offset:64
	global_load_ushort v195, v66, s[6:7] offset:64
	global_load_ushort v196, v66, s[0:1] offset:1024
	global_load_ushort v197, v66, s[4:5] offset:1024
	global_load_ushort v198, v66, s[6:7] offset:1024
	global_load_ushort v199, v66, s[0:1] offset:1088
	global_load_ushort v200, v66, s[4:5] offset:1088
	global_load_ushort v201, v66, s[6:7] offset:1088
	global_load_ushort v202, v66, s[0:1] offset:2048
	global_load_ushort v203, v66, s[4:5] offset:2048
	global_load_ushort v204, v66, s[6:7] offset:2048
	global_load_ushort v205, v66, s[0:1] offset:2112
	global_load_ushort v206, v66, s[4:5] offset:2112
	global_load_ushort v207, v66, s[6:7] offset:2112
	global_load_ushort v208, v66, s[0:1] offset:3072
	global_load_ushort v209, v66, s[4:5] offset:3072
	global_load_ushort v210, v66, s[6:7] offset:3072
	global_load_ushort v211, v66, s[0:1] offset:3136
	global_load_ushort v212, v66, s[4:5] offset:3136
	global_load_ushort v213, v66, s[6:7] offset:3136
	s_waitcnt vmcnt(53)
	v_lshlrev_b32_e32 v214, 16, v214
	v_lshlrev_b32_e32 v215, 16, v215
	v_lshlrev_b32_e32 v216, 16, v216
	v_fmac_f32_e32 v215, v68, v214
	v_add_f32_e32 v214, v215, v216
	v_mul_f32_e32 v215, 0x3d372713, v214
	v_mul_f32_e32 v215, v214, v215
	v_fma_f32 v215, v214, v215, v214
	v_mul_f32_e32 v215, 0xbfcc422a, v215
	v_mul_f32_e32 v215, 0x3fb8aa3b, v215
	v_exp_f32_e32 v215, v215
	v_mul_f32_e32 v20, 0xbfb8aa3b, v20
	v_exp_f32_e32 v20, v20
	v_add_f32_e32 v215, 1.0, v215
	v_add_f32_e32 v20, 1.0, v20
	v_rcp_f32_e32 v215, v215
	v_rcp_f32_e32 v20, v20
	v_mul_f32_e32 v214, v214, v215
	v_mul_f32_e32 v214, v20, v214
	v_cvt_pk_bf16_f32 v214, v214, v214
	global_store_short v67, v214, s[10:11]
	s_waitcnt vmcnt(51)
	v_lshlrev_b32_e32 v217, 16, v217
	v_lshlrev_b32_e32 v218, 16, v218
	v_lshlrev_b32_e32 v219, 16, v219
	v_fmac_f32_e32 v218, v69, v217
	v_add_f32_e32 v217, v218, v219
	v_mul_f32_e32 v218, 0x3d372713, v217
	v_mul_f32_e32 v218, v217, v218
	v_fma_f32 v218, v217, v218, v217
	v_mul_f32_e32 v218, 0xbfcc422a, v218
	v_mul_f32_e32 v218, 0x3fb8aa3b, v218
	v_exp_f32_e32 v218, v218
	v_mul_f32_e32 v4, 0xbfb8aa3b, v4
	v_exp_f32_e32 v4, v4
	v_add_f32_e32 v218, 1.0, v218
	v_add_f32_e32 v4, 1.0, v4
	v_rcp_f32_e32 v218, v218
	v_rcp_f32_e32 v4, v4
	v_mul_f32_e32 v217, v217, v218
	v_mul_f32_e32 v217, v4, v217
	v_cvt_pk_bf16_f32 v217, v217, v217
	global_store_short v67, v217, s[10:11] offset:64
	s_waitcnt vmcnt(49)
	v_lshlrev_b32_e32 v220, 16, v220
	v_lshlrev_b32_e32 v221, 16, v221
	v_lshlrev_b32_e32 v222, 16, v222
	v_fmac_f32_e32 v221, v68, v220
	v_add_f32_e32 v220, v221, v222
	v_mul_f32_e32 v221, 0x3d372713, v220
	v_mul_f32_e32 v221, v220, v221
	v_fma_f32 v221, v220, v221, v220
	v_mul_f32_e32 v221, 0xbfcc422a, v221
	v_mul_f32_e32 v221, 0x3fb8aa3b, v221
	v_exp_f32_e32 v221, v221
	v_mul_f32_e32 v21, 0xbfb8aa3b, v21
	v_exp_f32_e32 v21, v21
	v_add_f32_e32 v221, 1.0, v221
	v_add_f32_e32 v21, 1.0, v21
	v_rcp_f32_e32 v221, v221
	v_rcp_f32_e32 v21, v21
	v_mul_f32_e32 v220, v220, v221
	v_mul_f32_e32 v220, v21, v220
	v_cvt_pk_bf16_f32 v220, v220, v220
	global_store_short v67, v220, s[10:11] offset:1024
	s_waitcnt vmcnt(47)
	v_lshlrev_b32_e32 v223, 16, v223
	v_lshlrev_b32_e32 v224, 16, v224
	v_lshlrev_b32_e32 v225, 16, v225
	v_fmac_f32_e32 v224, v69, v223
	v_add_f32_e32 v223, v224, v225
	v_mul_f32_e32 v224, 0x3d372713, v223
	v_mul_f32_e32 v224, v223, v224
	v_fma_f32 v224, v223, v224, v223
	v_mul_f32_e32 v224, 0xbfcc422a, v224
	v_mul_f32_e32 v224, 0x3fb8aa3b, v224
	v_exp_f32_e32 v224, v224
	v_mul_f32_e32 v5, 0xbfb8aa3b, v5
	v_exp_f32_e32 v5, v5
	v_add_f32_e32 v224, 1.0, v224
	v_add_f32_e32 v5, 1.0, v5
	v_rcp_f32_e32 v224, v224
	v_rcp_f32_e32 v5, v5
	v_mul_f32_e32 v223, v223, v224
	v_mul_f32_e32 v223, v5, v223
	v_cvt_pk_bf16_f32 v223, v223, v223
	global_store_short v67, v223, s[10:11] offset:1088
	s_waitcnt vmcnt(45)
	v_lshlrev_b32_e32 v226, 16, v226
	v_lshlrev_b32_e32 v227, 16, v227
	v_lshlrev_b32_e32 v228, 16, v228
	v_fmac_f32_e32 v227, v68, v226
	v_add_f32_e32 v226, v227, v228
	v_mul_f32_e32 v227, 0x3d372713, v226
	v_mul_f32_e32 v227, v226, v227
	v_fma_f32 v227, v226, v227, v226
	v_mul_f32_e32 v227, 0xbfcc422a, v227
	v_mul_f32_e32 v227, 0x3fb8aa3b, v227
	v_exp_f32_e32 v227, v227
	v_mul_f32_e32 v22, 0xbfb8aa3b, v22
	v_exp_f32_e32 v22, v22
	v_add_f32_e32 v227, 1.0, v227
	v_add_f32_e32 v22, 1.0, v22
	v_rcp_f32_e32 v227, v227
	v_rcp_f32_e32 v22, v22
	v_mul_f32_e32 v226, v226, v227
	v_mul_f32_e32 v226, v22, v226
	v_cvt_pk_bf16_f32 v226, v226, v226
	global_store_short v67, v226, s[10:11] offset:2048
	s_waitcnt vmcnt(43)
	v_lshlrev_b32_e32 v229, 16, v229
	v_lshlrev_b32_e32 v230, 16, v230
	v_lshlrev_b32_e32 v231, 16, v231
	v_fmac_f32_e32 v230, v69, v229
	v_add_f32_e32 v229, v230, v231
	v_mul_f32_e32 v230, 0x3d372713, v229
	v_mul_f32_e32 v230, v229, v230
	v_fma_f32 v230, v229, v230, v229
	v_mul_f32_e32 v230, 0xbfcc422a, v230
	v_mul_f32_e32 v230, 0x3fb8aa3b, v230
	v_exp_f32_e32 v230, v230
	v_mul_f32_e32 v6, 0xbfb8aa3b, v6
	v_exp_f32_e32 v6, v6
	v_add_f32_e32 v230, 1.0, v230
	v_add_f32_e32 v6, 1.0, v6
	v_rcp_f32_e32 v230, v230
	v_rcp_f32_e32 v6, v6
	v_mul_f32_e32 v229, v229, v230
	v_mul_f32_e32 v229, v6, v229
	v_cvt_pk_bf16_f32 v229, v229, v229
	global_store_short v67, v229, s[10:11] offset:2112
	s_waitcnt vmcnt(41)
	v_lshlrev_b32_e32 v232, 16, v232
	v_lshlrev_b32_e32 v233, 16, v233
	v_lshlrev_b32_e32 v70, 16, v70
	v_fmac_f32_e32 v233, v68, v232
	v_add_f32_e32 v232, v233, v70
	v_mul_f32_e32 v233, 0x3d372713, v232
	v_mul_f32_e32 v233, v232, v233
	v_fma_f32 v233, v232, v233, v232
	v_mul_f32_e32 v233, 0xbfcc422a, v233
	v_mul_f32_e32 v233, 0x3fb8aa3b, v233
	v_exp_f32_e32 v233, v233
	v_mul_f32_e32 v23, 0xbfb8aa3b, v23
	v_exp_f32_e32 v23, v23
	v_add_f32_e32 v233, 1.0, v233
	v_add_f32_e32 v23, 1.0, v23
	v_rcp_f32_e32 v233, v233
	v_rcp_f32_e32 v23, v23
	v_mul_f32_e32 v232, v232, v233
	v_mul_f32_e32 v232, v23, v232
	v_cvt_pk_bf16_f32 v232, v232, v232
	global_store_short v67, v232, s[10:11] offset:3072
	s_waitcnt vmcnt(39)
	v_lshlrev_b32_e32 v71, 16, v71
	v_lshlrev_b32_e32 v72, 16, v72
	v_lshlrev_b32_e32 v73, 16, v73
	v_fmac_f32_e32 v72, v69, v71
	v_add_f32_e32 v71, v72, v73
	v_mul_f32_e32 v72, 0x3d372713, v71
	v_mul_f32_e32 v72, v71, v72
	v_fma_f32 v72, v71, v72, v71
	v_mul_f32_e32 v72, 0xbfcc422a, v72
	v_mul_f32_e32 v72, 0x3fb8aa3b, v72
	v_exp_f32_e32 v72, v72
	v_mul_f32_e32 v7, 0xbfb8aa3b, v7
	v_exp_f32_e32 v7, v7
	v_add_f32_e32 v72, 1.0, v72
	v_add_f32_e32 v7, 1.0, v7
	v_rcp_f32_e32 v72, v72
	v_rcp_f32_e32 v7, v7
	v_mul_f32_e32 v71, v71, v72
	v_mul_f32_e32 v71, v7, v71
	v_cvt_pk_bf16_f32 v71, v71, v71
	global_store_short v67, v71, s[10:11] offset:3136
	v_add_u32_e32 v67, 0xe000, v65
	global_load_ushort v214, v67, s[0:1]
	global_load_ushort v215, v67, s[4:5]
	global_load_ushort v216, v67, s[6:7]
	global_load_ushort v217, v67, s[0:1] offset:64
	global_load_ushort v218, v67, s[4:5] offset:64
	global_load_ushort v219, v67, s[6:7] offset:64
	global_load_ushort v220, v67, s[0:1] offset:1024
	global_load_ushort v221, v67, s[4:5] offset:1024
	global_load_ushort v222, v67, s[6:7] offset:1024
	global_load_ushort v223, v67, s[0:1] offset:1088
	global_load_ushort v224, v67, s[4:5] offset:1088
	global_load_ushort v225, v67, s[6:7] offset:1088
	global_load_ushort v226, v67, s[0:1] offset:2048
	global_load_ushort v227, v67, s[4:5] offset:2048
	global_load_ushort v228, v67, s[6:7] offset:2048
	global_load_ushort v229, v67, s[0:1] offset:2112
	global_load_ushort v230, v67, s[4:5] offset:2112
	global_load_ushort v231, v67, s[6:7] offset:2112
	global_load_ushort v232, v67, s[0:1] offset:3072
	global_load_ushort v233, v67, s[4:5] offset:3072
	global_load_ushort v70, v67, s[6:7] offset:3072
	global_load_ushort v71, v67, s[0:1] offset:3136
	global_load_ushort v72, v67, s[4:5] offset:3136
	global_load_ushort v73, v67, s[6:7] offset:3136
	s_waitcnt vmcnt(53)
	v_lshlrev_b32_e32 v190, 16, v190
	v_lshlrev_b32_e32 v191, 16, v191
	v_lshlrev_b32_e32 v192, 16, v192
	v_fmac_f32_e32 v191, v68, v190
	v_add_f32_e32 v190, v191, v192
	v_mul_f32_e32 v191, 0x3d372713, v190
	v_mul_f32_e32 v191, v190, v191
	v_fma_f32 v191, v190, v191, v190
	v_mul_f32_e32 v191, 0xbfcc422a, v191
	v_mul_f32_e32 v191, 0x3fb8aa3b, v191
	v_exp_f32_e32 v191, v191
	v_mul_f32_e32 v24, 0xbfb8aa3b, v24
	v_exp_f32_e32 v24, v24
	v_add_f32_e32 v191, 1.0, v191
	v_add_f32_e32 v24, 1.0, v24
	v_rcp_f32_e32 v191, v191
	v_rcp_f32_e32 v24, v24
	v_mul_f32_e32 v190, v190, v191
	v_mul_f32_e32 v190, v24, v190
	v_cvt_pk_bf16_f32 v190, v190, v190
	global_store_short v66, v190, s[10:11]
	s_waitcnt vmcnt(51)
	v_lshlrev_b32_e32 v193, 16, v193
	v_lshlrev_b32_e32 v194, 16, v194
	v_lshlrev_b32_e32 v195, 16, v195
	v_fmac_f32_e32 v194, v69, v193
	v_add_f32_e32 v193, v194, v195
	v_mul_f32_e32 v194, 0x3d372713, v193
	v_mul_f32_e32 v194, v193, v194
	v_fma_f32 v194, v193, v194, v193
	v_mul_f32_e32 v194, 0xbfcc422a, v194
	v_mul_f32_e32 v194, 0x3fb8aa3b, v194
	v_exp_f32_e32 v194, v194
	v_mul_f32_e32 v8, 0xbfb8aa3b, v8
	v_exp_f32_e32 v8, v8
	v_add_f32_e32 v194, 1.0, v194
	v_add_f32_e32 v8, 1.0, v8
	v_rcp_f32_e32 v194, v194
	v_rcp_f32_e32 v8, v8
	v_mul_f32_e32 v193, v193, v194
	v_mul_f32_e32 v193, v8, v193
	v_cvt_pk_bf16_f32 v193, v193, v193
	global_store_short v66, v193, s[10:11] offset:64
	s_waitcnt vmcnt(49)
	v_lshlrev_b32_e32 v196, 16, v196
	v_lshlrev_b32_e32 v197, 16, v197
	v_lshlrev_b32_e32 v198, 16, v198
	v_fmac_f32_e32 v197, v68, v196
	v_add_f32_e32 v196, v197, v198
	v_mul_f32_e32 v197, 0x3d372713, v196
	v_mul_f32_e32 v197, v196, v197
	v_fma_f32 v197, v196, v197, v196
	v_mul_f32_e32 v197, 0xbfcc422a, v197
	v_mul_f32_e32 v197, 0x3fb8aa3b, v197
	v_exp_f32_e32 v197, v197
	v_mul_f32_e32 v25, 0xbfb8aa3b, v25
	v_exp_f32_e32 v25, v25
	v_add_f32_e32 v197, 1.0, v197
	v_add_f32_e32 v25, 1.0, v25
	v_rcp_f32_e32 v197, v197
	v_rcp_f32_e32 v25, v25
	v_mul_f32_e32 v196, v196, v197
	v_mul_f32_e32 v196, v25, v196
	v_cvt_pk_bf16_f32 v196, v196, v196
	global_store_short v66, v196, s[10:11] offset:1024
	s_waitcnt vmcnt(47)
	v_lshlrev_b32_e32 v199, 16, v199
	v_lshlrev_b32_e32 v200, 16, v200
	v_lshlrev_b32_e32 v201, 16, v201
	v_fmac_f32_e32 v200, v69, v199
	v_add_f32_e32 v199, v200, v201
	v_mul_f32_e32 v200, 0x3d372713, v199
	v_mul_f32_e32 v200, v199, v200
	v_fma_f32 v200, v199, v200, v199
	v_mul_f32_e32 v200, 0xbfcc422a, v200
	v_mul_f32_e32 v200, 0x3fb8aa3b, v200
	v_exp_f32_e32 v200, v200
	v_mul_f32_e32 v9, 0xbfb8aa3b, v9
	v_exp_f32_e32 v9, v9
	v_add_f32_e32 v200, 1.0, v200
	v_add_f32_e32 v9, 1.0, v9
	v_rcp_f32_e32 v200, v200
	v_rcp_f32_e32 v9, v9
	v_mul_f32_e32 v199, v199, v200
	v_mul_f32_e32 v199, v9, v199
	v_cvt_pk_bf16_f32 v199, v199, v199
	global_store_short v66, v199, s[10:11] offset:1088
	s_waitcnt vmcnt(45)
	v_lshlrev_b32_e32 v202, 16, v202
	v_lshlrev_b32_e32 v203, 16, v203
	v_lshlrev_b32_e32 v204, 16, v204
	v_fmac_f32_e32 v203, v68, v202
	v_add_f32_e32 v202, v203, v204
	v_mul_f32_e32 v203, 0x3d372713, v202
	v_mul_f32_e32 v203, v202, v203
	v_fma_f32 v203, v202, v203, v202
	v_mul_f32_e32 v203, 0xbfcc422a, v203
	v_mul_f32_e32 v203, 0x3fb8aa3b, v203
	v_exp_f32_e32 v203, v203
	v_mul_f32_e32 v26, 0xbfb8aa3b, v26
	v_exp_f32_e32 v26, v26
	v_add_f32_e32 v203, 1.0, v203
	v_add_f32_e32 v26, 1.0, v26
	v_rcp_f32_e32 v203, v203
	v_rcp_f32_e32 v26, v26
	v_mul_f32_e32 v202, v202, v203
	v_mul_f32_e32 v202, v26, v202
	v_cvt_pk_bf16_f32 v202, v202, v202
	global_store_short v66, v202, s[10:11] offset:2048
	s_waitcnt vmcnt(43)
	v_lshlrev_b32_e32 v205, 16, v205
	v_lshlrev_b32_e32 v206, 16, v206
	v_lshlrev_b32_e32 v207, 16, v207
	v_fmac_f32_e32 v206, v69, v205
	v_add_f32_e32 v205, v206, v207
	v_mul_f32_e32 v206, 0x3d372713, v205
	v_mul_f32_e32 v206, v205, v206
	v_fma_f32 v206, v205, v206, v205
	v_mul_f32_e32 v206, 0xbfcc422a, v206
	v_mul_f32_e32 v206, 0x3fb8aa3b, v206
	v_exp_f32_e32 v206, v206
	v_mul_f32_e32 v10, 0xbfb8aa3b, v10
	v_exp_f32_e32 v10, v10
	v_add_f32_e32 v206, 1.0, v206
	v_add_f32_e32 v10, 1.0, v10
	v_rcp_f32_e32 v206, v206
	v_rcp_f32_e32 v10, v10
	v_mul_f32_e32 v205, v205, v206
	v_mul_f32_e32 v205, v10, v205
	v_cvt_pk_bf16_f32 v205, v205, v205
	global_store_short v66, v205, s[10:11] offset:2112
	s_waitcnt vmcnt(41)
	v_lshlrev_b32_e32 v208, 16, v208
	v_lshlrev_b32_e32 v209, 16, v209
	v_lshlrev_b32_e32 v210, 16, v210
	v_fmac_f32_e32 v209, v68, v208
	v_add_f32_e32 v208, v209, v210
	v_mul_f32_e32 v209, 0x3d372713, v208
	v_mul_f32_e32 v209, v208, v209
	v_fma_f32 v209, v208, v209, v208
	v_mul_f32_e32 v209, 0xbfcc422a, v209
	v_mul_f32_e32 v209, 0x3fb8aa3b, v209
	v_exp_f32_e32 v209, v209
	v_mul_f32_e32 v27, 0xbfb8aa3b, v27
	v_exp_f32_e32 v27, v27
	v_add_f32_e32 v209, 1.0, v209
	v_add_f32_e32 v27, 1.0, v27
	v_rcp_f32_e32 v209, v209
	v_rcp_f32_e32 v27, v27
	v_mul_f32_e32 v208, v208, v209
	v_mul_f32_e32 v208, v27, v208
	v_cvt_pk_bf16_f32 v208, v208, v208
	global_store_short v66, v208, s[10:11] offset:3072
	s_waitcnt vmcnt(39)
	v_lshlrev_b32_e32 v211, 16, v211
	v_lshlrev_b32_e32 v212, 16, v212
	v_lshlrev_b32_e32 v213, 16, v213
	v_fmac_f32_e32 v212, v69, v211
	v_add_f32_e32 v211, v212, v213
	v_mul_f32_e32 v212, 0x3d372713, v211
	v_mul_f32_e32 v212, v211, v212
	v_fma_f32 v212, v211, v212, v211
	v_mul_f32_e32 v212, 0xbfcc422a, v212
	v_mul_f32_e32 v212, 0x3fb8aa3b, v212
	v_exp_f32_e32 v212, v212
	v_mul_f32_e32 v11, 0xbfb8aa3b, v11
	v_exp_f32_e32 v11, v11
	v_add_f32_e32 v212, 1.0, v212
	v_add_f32_e32 v11, 1.0, v11
	v_rcp_f32_e32 v212, v212
	v_rcp_f32_e32 v11, v11
	v_mul_f32_e32 v211, v211, v212
	v_mul_f32_e32 v211, v11, v211
	v_cvt_pk_bf16_f32 v211, v211, v211
	global_store_short v66, v211, s[10:11] offset:3136
	s_waitcnt vmcnt(29)
	v_lshlrev_b32_e32 v214, 16, v214
	v_lshlrev_b32_e32 v215, 16, v215
	v_lshlrev_b32_e32 v216, 16, v216
	v_fmac_f32_e32 v215, v68, v214
	v_add_f32_e32 v214, v215, v216
	v_mul_f32_e32 v215, 0x3d372713, v214
	v_mul_f32_e32 v215, v214, v215
	v_fma_f32 v215, v214, v215, v214
	v_mul_f32_e32 v215, 0xbfcc422a, v215
	v_mul_f32_e32 v215, 0x3fb8aa3b, v215
	v_exp_f32_e32 v215, v215
	v_mul_f32_e32 v28, 0xbfb8aa3b, v28
	v_exp_f32_e32 v28, v28
	v_add_f32_e32 v215, 1.0, v215
	v_add_f32_e32 v28, 1.0, v28
	v_rcp_f32_e32 v215, v215
	v_rcp_f32_e32 v28, v28
	v_mul_f32_e32 v214, v214, v215
	v_mul_f32_e32 v214, v28, v214
	v_cvt_pk_bf16_f32 v214, v214, v214
	global_store_short v67, v214, s[10:11]
	s_waitcnt vmcnt(27)
	v_lshlrev_b32_e32 v217, 16, v217
	v_lshlrev_b32_e32 v218, 16, v218
	v_lshlrev_b32_e32 v219, 16, v219
	v_fmac_f32_e32 v218, v69, v217
	v_add_f32_e32 v217, v218, v219
	v_mul_f32_e32 v218, 0x3d372713, v217
	v_mul_f32_e32 v218, v217, v218
	v_fma_f32 v218, v217, v218, v217
	v_mul_f32_e32 v218, 0xbfcc422a, v218
	v_mul_f32_e32 v218, 0x3fb8aa3b, v218
	v_exp_f32_e32 v218, v218
	v_mul_f32_e32 v12, 0xbfb8aa3b, v12
	v_exp_f32_e32 v12, v12
	v_add_f32_e32 v218, 1.0, v218
	v_add_f32_e32 v12, 1.0, v12
	v_rcp_f32_e32 v218, v218
	v_rcp_f32_e32 v12, v12
	v_mul_f32_e32 v217, v217, v218
	v_mul_f32_e32 v217, v12, v217
	v_cvt_pk_bf16_f32 v217, v217, v217
	global_store_short v67, v217, s[10:11] offset:64
	s_waitcnt vmcnt(25)
	v_lshlrev_b32_e32 v220, 16, v220
	v_lshlrev_b32_e32 v221, 16, v221
	v_lshlrev_b32_e32 v222, 16, v222
	v_fmac_f32_e32 v221, v68, v220
	v_add_f32_e32 v220, v221, v222
	v_mul_f32_e32 v221, 0x3d372713, v220
	v_mul_f32_e32 v221, v220, v221
	v_fma_f32 v221, v220, v221, v220
	v_mul_f32_e32 v221, 0xbfcc422a, v221
	v_mul_f32_e32 v221, 0x3fb8aa3b, v221
	v_exp_f32_e32 v221, v221
	v_mul_f32_e32 v29, 0xbfb8aa3b, v29
	v_exp_f32_e32 v29, v29
	v_add_f32_e32 v221, 1.0, v221
	v_add_f32_e32 v29, 1.0, v29
	v_rcp_f32_e32 v221, v221
	v_rcp_f32_e32 v29, v29
	v_mul_f32_e32 v220, v220, v221
	v_mul_f32_e32 v220, v29, v220
	v_cvt_pk_bf16_f32 v220, v220, v220
	global_store_short v67, v220, s[10:11] offset:1024
	s_waitcnt vmcnt(23)
	v_lshlrev_b32_e32 v223, 16, v223
	v_lshlrev_b32_e32 v224, 16, v224
	v_lshlrev_b32_e32 v225, 16, v225
	v_fmac_f32_e32 v224, v69, v223
	v_add_f32_e32 v223, v224, v225
	v_mul_f32_e32 v224, 0x3d372713, v223
	v_mul_f32_e32 v224, v223, v224
	v_fma_f32 v224, v223, v224, v223
	v_mul_f32_e32 v224, 0xbfcc422a, v224
	v_mul_f32_e32 v224, 0x3fb8aa3b, v224
	v_exp_f32_e32 v224, v224
	v_mul_f32_e32 v13, 0xbfb8aa3b, v13
	v_exp_f32_e32 v13, v13
	v_add_f32_e32 v224, 1.0, v224
	v_add_f32_e32 v13, 1.0, v13
	v_rcp_f32_e32 v224, v224
	v_rcp_f32_e32 v13, v13
	v_mul_f32_e32 v223, v223, v224
	v_mul_f32_e32 v223, v13, v223
	v_cvt_pk_bf16_f32 v223, v223, v223
	global_store_short v67, v223, s[10:11] offset:1088
	s_waitcnt vmcnt(21)
	v_lshlrev_b32_e32 v226, 16, v226
	v_lshlrev_b32_e32 v227, 16, v227
	v_lshlrev_b32_e32 v228, 16, v228
	v_fmac_f32_e32 v227, v68, v226
	v_add_f32_e32 v226, v227, v228
	v_mul_f32_e32 v227, 0x3d372713, v226
	v_mul_f32_e32 v227, v226, v227
	v_fma_f32 v227, v226, v227, v226
	v_mul_f32_e32 v227, 0xbfcc422a, v227
	v_mul_f32_e32 v227, 0x3fb8aa3b, v227
	v_exp_f32_e32 v227, v227
	v_mul_f32_e32 v30, 0xbfb8aa3b, v30
	v_exp_f32_e32 v30, v30
	v_add_f32_e32 v227, 1.0, v227
	v_add_f32_e32 v30, 1.0, v30
	v_rcp_f32_e32 v227, v227
	v_rcp_f32_e32 v30, v30
	v_mul_f32_e32 v226, v226, v227
	v_mul_f32_e32 v226, v30, v226
	v_cvt_pk_bf16_f32 v226, v226, v226
	global_store_short v67, v226, s[10:11] offset:2048
	s_waitcnt vmcnt(19)
	v_lshlrev_b32_e32 v229, 16, v229
	v_lshlrev_b32_e32 v230, 16, v230
	v_lshlrev_b32_e32 v231, 16, v231
	v_fmac_f32_e32 v230, v69, v229
	v_add_f32_e32 v229, v230, v231
	v_mul_f32_e32 v230, 0x3d372713, v229
	v_mul_f32_e32 v230, v229, v230
	v_fma_f32 v230, v229, v230, v229
	v_mul_f32_e32 v230, 0xbfcc422a, v230
	v_mul_f32_e32 v230, 0x3fb8aa3b, v230
	v_exp_f32_e32 v230, v230
	v_mul_f32_e32 v14, 0xbfb8aa3b, v14
	v_exp_f32_e32 v14, v14
	v_add_f32_e32 v230, 1.0, v230
	v_add_f32_e32 v14, 1.0, v14
	v_rcp_f32_e32 v230, v230
	v_rcp_f32_e32 v14, v14
	v_mul_f32_e32 v229, v229, v230
	v_mul_f32_e32 v229, v14, v229
	v_cvt_pk_bf16_f32 v229, v229, v229
	global_store_short v67, v229, s[10:11] offset:2112
	s_waitcnt vmcnt(17)
	v_lshlrev_b32_e32 v232, 16, v232
	v_lshlrev_b32_e32 v233, 16, v233
	v_lshlrev_b32_e32 v70, 16, v70
	v_fmac_f32_e32 v233, v68, v232
	v_add_f32_e32 v232, v233, v70
	v_mul_f32_e32 v233, 0x3d372713, v232
	v_mul_f32_e32 v233, v232, v233
	v_fma_f32 v233, v232, v233, v232
	v_mul_f32_e32 v233, 0xbfcc422a, v233
	v_mul_f32_e32 v233, 0x3fb8aa3b, v233
	v_exp_f32_e32 v233, v233
	v_mul_f32_e32 v31, 0xbfb8aa3b, v31
	v_exp_f32_e32 v31, v31
	v_add_f32_e32 v233, 1.0, v233
	v_add_f32_e32 v31, 1.0, v31
	v_rcp_f32_e32 v233, v233
	v_rcp_f32_e32 v31, v31
	v_mul_f32_e32 v232, v232, v233
	v_mul_f32_e32 v232, v31, v232
	v_cvt_pk_bf16_f32 v232, v232, v232
	global_store_short v67, v232, s[10:11] offset:3072
	s_waitcnt vmcnt(15)
	v_lshlrev_b32_e32 v71, 16, v71
	v_lshlrev_b32_e32 v72, 16, v72
	v_lshlrev_b32_e32 v73, 16, v73
	v_fmac_f32_e32 v72, v69, v71
	v_add_f32_e32 v71, v72, v73
	v_mul_f32_e32 v72, 0x3d372713, v71
	v_mul_f32_e32 v72, v71, v72
	v_fma_f32 v72, v71, v72, v71
	v_mul_f32_e32 v72, 0xbfcc422a, v72
	v_mul_f32_e32 v72, 0x3fb8aa3b, v72
	v_exp_f32_e32 v72, v72
	v_mul_f32_e32 v15, 0xbfb8aa3b, v15
	v_exp_f32_e32 v15, v15
	v_add_f32_e32 v72, 1.0, v72
	v_add_f32_e32 v15, 1.0, v15
	v_rcp_f32_e32 v72, v72
	v_rcp_f32_e32 v15, v15
	v_mul_f32_e32 v71, v71, v72
	v_mul_f32_e32 v71, v15, v71
	v_cvt_pk_bf16_f32 v71, v71, v71
	global_store_short v67, v71, s[10:11] offset:3136
	s_add_i32 s36, s36, s20
	s_add_i32 s22, s22, s23
	s_add_i32 s24, s24, s25
	s_cmp_gt_i32 s36, 31
	v_readlane_b32 s41, v251, 24
	v_readlane_b32 s44, v251, 27
	v_readlane_b32 s45, v251, 28
	v_readlane_b32 s48, v251, 31
	v_readlane_b32 s49, v251, 32
	v_readlane_b32 s50, v251, 33
	v_readlane_b32 s51, v251, 34
	v_readlane_b32 s52, v251, 35
	v_readlane_b32 s53, v251, 36
	v_readlane_b32 s54, v251, 37
	v_readlane_b32 s55, v251, 38
	s_cbranch_scc1 .LBB0_3650
